# prep: bias1 dot loop + mod loop double-buffered loads; first phase seam uses the counter grid barrier instead of cooperative-groups sync
# speedup vs baseline: 1.0374x; 1.0030x over previous
.LBB0_23:
	v_readlane_b32 s4, v252, 24
	v_readlane_b32 s0, v253, 0
	s_add_i32 s2, s4, 1
	v_readlane_b32 s1, v253, 1
	s_cmp_ge_i32 s2, s1
	s_mov_b64 s[0:1], -1
	v_readlane_b32 s18, v252, 23
	s_mov_b32 s14, 0x800000
	s_cbranch_scc1 .LBB0_7
	v_readlane_b32 s0, v253, 0
	v_readlane_b32 s1, v253, 1
	s_cmp_lg_u32 s4, s0
	s_mov_b64 s[0:1], -1
	s_nop 0
	v_readlane_b32 s4, v253, 27
	v_readlane_b32 s0, v252, 1
	v_readlane_b32 s5, v253, 28
	s_add_i32 s8, s0, 1
	s_mov_b64 s[0:1], -1
	s_and_b64 vcc, exec, s[4:5]
	s_cbranch_vccz .LBB0_32
	v_mov_b32_e32 v0, 0xe8
	s_nop 0
	v_add_u32_e32 v0, 0, v0
	v_add_u32_e32 v0, 0x20400, v0
	ds_read_b64 v[0:1], v0
	s_waitcnt lgkmcnt(0)
	s_barrier
	v_readfirstlane_b32 s5, v1
	v_readfirstlane_b32 s4, v0
	s_mov_b64 s[0:1], exec
	v_readlane_b32 s6, v253, 2
	v_readlane_b32 s7, v253, 3
	s_and_b64 s[6:7], s[0:1], s[6:7]
	s_mov_b64 exec, s[6:7]
	s_cbranch_execz .LBB0_31
	v_mov_b64_e32 v[0:1], s[4:5]
	buffer_wbl2 sc1
	s_waitcnt vmcnt(0)
	buffer_inv sc1
	global_atomic_add v[0:1], v210, off offset:512
	global_load_dword v0, v[0:1], off offset:512 sc1
	s_mul_i32 s9, s78, s8
	s_waitcnt vmcnt(0) lgkmcnt(0)
	v_cmp_gt_u32_e32 vcc, s9, v0
	s_and_b64 exec, exec, vcc
	s_cbranch_execz .LBB0_30
	s_mov_b64 s[6:7], 0

.LBB0_575:
	s_lshl_b32 s12, s10, 10
	s_and_b32 s82, s12, 0xfffff800
	s_and_b32 s12, s14, 1
	s_lshl_b64 s[0:1], s[10:11], 18
	s_lshl_b32 s13, s12, 3
	s_and_b32 s1, s1, 0x3ffff
	s_and_b32 s0, s0, 0xfff80000
	s_addk_i32 s13, 0x78
	v_mov_b32_e32 v4, s13
	s_cmp_eq_u32 s12, 0
	s_movk_i32 s12, 0x88
	s_cselect_b32 s12, s12, 0x98
	v_add_u32_e32 v4, s91, v4
	v_mov_b32_e32 v6, s12
	ds_read_b64 v[4:5], v4
	v_mov_b32_e32 v8, 0
	v_add_u32_e32 v6, s91, v6
	ds_read_b64 v[6:7], v6
	s_waitcnt lgkmcnt(0)
	v_readfirstlane_b32 s13, v5
	v_readfirstlane_b32 s12, v4
	v_mov_b32_e32 v9, v37
	v_readfirstlane_b32 s17, v7
	v_readfirstlane_b32 s16, v6
	v_lshl_add_u64 v[6:7], s[12:13], 0, v[2:3]
	v_lshl_add_u64 v[6:7], s[82:83], 2, v[6:7]
	v_lshl_add_u64 v[4:5], s[16:17], 0, v[0:1]
	v_lshl_add_u64 v[4:5], v[4:5], 0, s[0:1]
	s_mov_b64 s[0:1], 0
	s_waitcnt lgkmcnt(0)
	s_movk_i32 s12, 16
.LBB0_576:
	global_load_dword v78, v[6:7], off
	global_load_dword v94, v[4:5], off
	global_load_dword v79, v[6:7], off offset:4
	global_load_dword v95, v[4:5], off offset:256
	global_load_dword v80, v[6:7], off offset:8
	global_load_dword v96, v[4:5], off offset:512
	global_load_dword v81, v[6:7], off offset:12
	global_load_dword v97, v[4:5], off offset:768
	global_load_dword v82, v[6:7], off offset:16
	global_load_dword v98, v[4:5], off offset:1024
	global_load_dword v83, v[6:7], off offset:20
	global_load_dword v99, v[4:5], off offset:1280
	global_load_dword v84, v[6:7], off offset:24
	global_load_dword v100, v[4:5], off offset:1536
	global_load_dword v85, v[6:7], off offset:28
	global_load_dword v101, v[4:5], off offset:1792
	global_load_dword v86, v[6:7], off offset:32
	global_load_dword v102, v[4:5], off offset:2048
	global_load_dword v87, v[6:7], off offset:36
	global_load_dword v103, v[4:5], off offset:2304
	global_load_dword v88, v[6:7], off offset:40
	global_load_dword v104, v[4:5], off offset:2560
	global_load_dword v89, v[6:7], off offset:44
	global_load_dword v105, v[4:5], off offset:2816
	global_load_dword v90, v[6:7], off offset:48
	global_load_dword v106, v[4:5], off offset:3072
	global_load_dword v91, v[6:7], off offset:52
	global_load_dword v107, v[4:5], off offset:3328
	global_load_dword v92, v[6:7], off offset:56
	global_load_dword v108, v[4:5], off offset:3584
	global_load_dword v93, v[6:7], off offset:60
	global_load_dword v109, v[4:5], off offset:3840
	v_lshl_add_u64 v[6:7], v[6:7], 0, 64
	v_add_co_u32_e32 v4, vcc, 0x1000, v4
	s_nop 1
	v_addc_co_u32_e32 v5, vcc, 0, v5, vcc
	s_waitcnt vmcnt(30)
	v_fmac_f32_e32 v8, v78, v94
	s_waitcnt vmcnt(28)
	v_fmac_f32_e32 v8, v79, v95
	s_waitcnt vmcnt(26)
	v_fmac_f32_e32 v8, v80, v96
	s_waitcnt vmcnt(24)
	v_fmac_f32_e32 v8, v81, v97
	s_waitcnt vmcnt(22)
	v_fmac_f32_e32 v8, v82, v98
	s_waitcnt vmcnt(20)
	v_fmac_f32_e32 v8, v83, v99
	s_waitcnt vmcnt(18)
	v_fmac_f32_e32 v8, v84, v100
	s_waitcnt vmcnt(16)
	v_fmac_f32_e32 v8, v85, v101
	s_waitcnt vmcnt(14)
	v_fmac_f32_e32 v8, v86, v102
	s_waitcnt vmcnt(12)
	v_fmac_f32_e32 v8, v87, v103
	s_waitcnt vmcnt(10)
	v_fmac_f32_e32 v8, v88, v104
	s_waitcnt vmcnt(8)
	v_fmac_f32_e32 v8, v89, v105
	s_waitcnt vmcnt(6)
	v_fmac_f32_e32 v8, v90, v106
	s_waitcnt vmcnt(4)
	v_fmac_f32_e32 v8, v91, v107
	s_waitcnt vmcnt(2)
	v_fmac_f32_e32 v8, v92, v108
	s_waitcnt vmcnt(0)
	v_fmac_f32_e32 v8, v93, v109
	s_sub_u32 s12, s12, 1
	s_cmp_lg_u32 s12, 0
	s_cbranch_scc1 .LBB0_576
	s_mov_b64 s[12:13], 0x100
	s_or_b64 exec, exec, s[0:1]
	s_barrier
	ds_write_b32 v18, v8
	s_waitcnt lgkmcnt(0)
	s_barrier
	s_and_saveexec_b64 s[0:1], s[4:5]
	s_cbranch_execz .LBB0_579
	ds_read2st64_b32 v[4:5], v18 offset1:1
	ds_read2st64_b32 v[6:7], v18 offset0:2 offset1:3
	ds_read2st64_b32 v[8:9], v18 offset0:4 offset1:5
	ds_read2st64_b32 v[10:11], v18 offset0:6 offset1:7
	s_add_i32 s12, s14, s56
	s_lshl_b32 s12, s12, 6
	s_addk_i32 s12, 0xe800
	s_waitcnt lgkmcnt(3)
	v_add_f32_e32 v4, 0, v4
	v_add_f32_e32 v4, v4, v5
	s_waitcnt lgkmcnt(2)
	v_add_f32_e32 v4, v4, v6
	v_add_f32_e32 v4, v4, v7
	s_waitcnt lgkmcnt(1)
	v_add_f32_e32 v4, v4, v8
	v_add_f32_e32 v4, v4, v9
	s_waitcnt lgkmcnt(0)
	v_add_f32_e32 v4, v4, v10
	v_add_f32_e32 v6, v4, v11
	v_add_u32_e32 v4, s12, v16
	v_ashrrev_i32_e32 v5, 31, v4
	v_lshl_add_u64 v[4:5], v[4:5], 2, s[8:9]
	global_store_dword v[4:5], v6, off

.LBB0_580:
	s_mul_hi_i32 s0, s14, 0x2aaaaaab
	s_lshr_b32 s1, s0, 31
	s_ashr_i32 s0, s0, 3
	s_add_i32 s0, s0, s1
	s_mul_i32 s1, s0, 48
	v_mov_b32_e32 v4, 8
	s_sub_i32 s16, s14, s1
	s_waitcnt lgkmcnt(0)
	s_barrier
	s_mul_i32 s1, s16, 43
	v_add_u32_e32 v4, s91, v4
	s_sext_i32_i16 s12, s1
	ds_read_b64 v[4:5], v4
	s_ashr_i32 s17, s12, 9
	s_bfe_u32 s1, s1, 0x1000f
	s_add_i32 s17, s17, s1
	s_sext_i32_i16 s15, s17
	v_lshl_or_b32 v8, s15, 13, v19
	s_waitcnt lgkmcnt(0)
	v_readfirstlane_b32 s1, v5
	v_readfirstlane_b32 s12, v4
	v_add_u32_e32 v6, v8, v21
	v_mov_b32_e32 v5, s1
	v_mov_b32_e32 v4, s12
	v_ashrrev_i32_e32 v7, 31, v6
	v_lshl_add_u64 v[4:5], v[6:7], 2, v[4:5]
	global_load_dword v4, v[4:5], off
	v_mov_b32_e32 v6, 8
	v_mov_b32_e32 v12, 32
	s_mul_i32 s17, s17, 12
	s_sub_i32 s16, s16, s17
	s_sext_i32_i8 s16, s16
	s_mul_i32 s20, s0, 0x1800000
	s_mul_hi_i32 s19, s0, 0x1800000
	s_mov_b32 s18, 0
	s_waitcnt vmcnt(0) lgkmcnt(0)
	v_mul_f32_e32 v5, 0xbfb8aa3b, v4
	v_exp_f32_e32 v5, v5
	s_nop 0
	v_add_f32_e32 v5, 1.0, v5
	v_rcp_f32_e32 v5, v5
	s_nop 0
	v_mul_f32_e32 v4, v4, v5
	ds_write_b32 v18, v4
	s_nop 0
	v_add_u32_e32 v4, s91, v6
	ds_read_b64 v[4:5], v4
	v_add_u32_e32 v6, v8, v22
	v_ashrrev_i32_e32 v7, 31, v6
	s_waitcnt lgkmcnt(0)
	v_readfirstlane_b32 s1, v5
	v_readfirstlane_b32 s12, v4
	s_nop 0
	v_mov_b32_e32 v5, s1
	v_mov_b32_e32 v4, s12
	v_lshl_add_u64 v[4:5], v[6:7], 2, v[4:5]
	global_load_dword v4, v[4:5], off
	v_mov_b32_e32 v6, 8
	s_waitcnt vmcnt(0) lgkmcnt(0)
	v_mul_f32_e32 v5, 0xbfb8aa3b, v4
	v_exp_f32_e32 v5, v5
	s_nop 0
	v_add_f32_e32 v5, 1.0, v5
	v_rcp_f32_e32 v5, v5
	s_nop 0
	v_mul_f32_e32 v4, v4, v5
	ds_write_b32 v18, v4 offset:2048
	s_nop 0
	v_add_u32_e32 v4, s91, v6
	ds_read_b64 v[4:5], v4
	v_add_u32_e32 v6, v8, v23
	v_ashrrev_i32_e32 v7, 31, v6
	s_waitcnt lgkmcnt(0)
	v_readfirstlane_b32 s1, v5
	v_readfirstlane_b32 s12, v4
	s_nop 0
	v_mov_b32_e32 v5, s1
	v_mov_b32_e32 v4, s12
	v_lshl_add_u64 v[4:5], v[6:7], 2, v[4:5]
	global_load_dword v4, v[4:5], off
	v_mov_b32_e32 v6, 8
	s_waitcnt vmcnt(0) lgkmcnt(0)
	v_mul_f32_e32 v5, 0xbfb8aa3b, v4
	v_exp_f32_e32 v5, v5
	s_nop 0
	v_add_f32_e32 v5, 1.0, v5
	v_rcp_f32_e32 v5, v5
	s_nop 0
	v_mul_f32_e32 v4, v4, v5
	ds_write_b32 v18, v4 offset:4096
	s_nop 0
	v_add_u32_e32 v4, s91, v6
	ds_read_b64 v[4:5], v4
	v_add_u32_e32 v6, v8, v24
	v_ashrrev_i32_e32 v7, 31, v6
	s_waitcnt lgkmcnt(0)
	v_readfirstlane_b32 s1, v5
	v_readfirstlane_b32 s12, v4
	s_nop 0
	v_mov_b32_e32 v5, s1
	v_mov_b32_e32 v4, s12
	v_lshl_add_u64 v[4:5], v[6:7], 2, v[4:5]
	global_load_dword v4, v[4:5], off
	v_mov_b32_e32 v6, 8
	s_waitcnt vmcnt(0) lgkmcnt(0)
	v_mul_f32_e32 v5, 0xbfb8aa3b, v4
	v_exp_f32_e32 v5, v5
	s_nop 0
	v_add_f32_e32 v5, 1.0, v5
	v_rcp_f32_e32 v5, v5
	s_nop 0
	v_mul_f32_e32 v4, v4, v5
	ds_write_b32 v18, v4 offset:6144
	s_nop 0
	v_add_u32_e32 v4, s91, v6
	ds_read_b64 v[4:5], v4
	v_add_u32_e32 v6, v8, v25
	v_ashrrev_i32_e32 v7, 31, v6
	s_waitcnt lgkmcnt(0)
	v_readfirstlane_b32 s1, v5
	v_readfirstlane_b32 s12, v4
	s_nop 0
	v_mov_b32_e32 v5, s1
	v_mov_b32_e32 v4, s12
	v_lshl_add_u64 v[4:5], v[6:7], 2, v[4:5]
	global_load_dword v4, v[4:5], off
	v_mov_b32_e32 v6, 8
	s_waitcnt vmcnt(0) lgkmcnt(0)
	v_mul_f32_e32 v5, 0xbfb8aa3b, v4
	v_exp_f32_e32 v5, v5
	s_nop 0
	v_add_f32_e32 v5, 1.0, v5
	v_rcp_f32_e32 v5, v5
	s_nop 0
	v_mul_f32_e32 v4, v4, v5
	ds_write_b32 v18, v4 offset:8192
	s_nop 0
	v_add_u32_e32 v4, s91, v6
	ds_read_b64 v[4:5], v4
	v_add_u32_e32 v6, v8, v26
	v_ashrrev_i32_e32 v7, 31, v6
	s_waitcnt lgkmcnt(0)
	v_readfirstlane_b32 s1, v5
	v_readfirstlane_b32 s12, v4
	s_nop 0
	v_mov_b32_e32 v5, s1
	v_mov_b32_e32 v4, s12
	v_lshl_add_u64 v[4:5], v[6:7], 2, v[4:5]
	global_load_dword v4, v[4:5], off
	v_mov_b32_e32 v6, 8
	s_waitcnt vmcnt(0) lgkmcnt(0)
	v_mul_f32_e32 v5, 0xbfb8aa3b, v4
	v_exp_f32_e32 v5, v5
	s_nop 0
	v_add_f32_e32 v5, 1.0, v5
	v_rcp_f32_e32 v5, v5
	s_nop 0
	v_mul_f32_e32 v4, v4, v5
	ds_write_b32 v18, v4 offset:10240
	s_nop 0
	v_add_u32_e32 v4, s91, v6
	ds_read_b64 v[4:5], v4
	v_add_u32_e32 v6, v8, v27
	v_ashrrev_i32_e32 v7, 31, v6
	s_waitcnt lgkmcnt(0)
	v_readfirstlane_b32 s1, v5
	v_readfirstlane_b32 s12, v4
	s_nop 0
	v_mov_b32_e32 v5, s1
	v_mov_b32_e32 v4, s12
	v_lshl_add_u64 v[4:5], v[6:7], 2, v[4:5]
	global_load_dword v4, v[4:5], off
	v_mov_b32_e32 v6, 8
	s_waitcnt vmcnt(0) lgkmcnt(0)
	v_mul_f32_e32 v5, 0xbfb8aa3b, v4
	v_exp_f32_e32 v5, v5
	s_nop 0
	v_add_f32_e32 v5, 1.0, v5
	v_rcp_f32_e32 v5, v5
	s_nop 0
	v_mul_f32_e32 v4, v4, v5
	ds_write_b32 v18, v4 offset:12288
	s_nop 0
	v_add_u32_e32 v4, s91, v6
	ds_read_b64 v[4:5], v4
	v_add_u32_e32 v6, v8, v28
	v_ashrrev_i32_e32 v7, 31, v6
	s_waitcnt lgkmcnt(0)
	v_readfirstlane_b32 s1, v5
	v_readfirstlane_b32 s12, v4
	s_nop 0
	v_mov_b32_e32 v5, s1
	v_mov_b32_e32 v4, s12
	v_lshl_add_u64 v[4:5], v[6:7], 2, v[4:5]
	global_load_dword v4, v[4:5], off
	v_mov_b32_e32 v6, 8
	s_waitcnt vmcnt(0) lgkmcnt(0)
	v_mul_f32_e32 v5, 0xbfb8aa3b, v4
	v_exp_f32_e32 v5, v5
	s_nop 0
	v_add_f32_e32 v5, 1.0, v5
	v_rcp_f32_e32 v5, v5
	s_nop 0
	v_mul_f32_e32 v4, v4, v5
	ds_write_b32 v18, v4 offset:14336
	s_nop 0
	v_add_u32_e32 v4, s91, v6
	ds_read_b64 v[4:5], v4
	v_add_u32_e32 v6, v8, v29
	v_ashrrev_i32_e32 v7, 31, v6
	s_waitcnt lgkmcnt(0)
	v_readfirstlane_b32 s1, v5
	v_readfirstlane_b32 s12, v4
	s_nop 0
	v_mov_b32_e32 v5, s1
	v_mov_b32_e32 v4, s12
	v_lshl_add_u64 v[4:5], v[6:7], 2, v[4:5]
	global_load_dword v4, v[4:5], off
	v_mov_b32_e32 v6, 8
	s_waitcnt vmcnt(0) lgkmcnt(0)
	v_mul_f32_e32 v5, 0xbfb8aa3b, v4
	v_exp_f32_e32 v5, v5
	s_nop 0
	v_add_f32_e32 v5, 1.0, v5
	v_rcp_f32_e32 v5, v5
	s_nop 0
	v_mul_f32_e32 v4, v4, v5
	ds_write_b32 v18, v4 offset:16384
	s_nop 0
	v_add_u32_e32 v4, s91, v6
	ds_read_b64 v[4:5], v4
	v_add_u32_e32 v6, v8, v30
	v_ashrrev_i32_e32 v7, 31, v6
	s_waitcnt lgkmcnt(0)
	v_readfirstlane_b32 s1, v5
	v_readfirstlane_b32 s12, v4
	s_nop 0
	v_mov_b32_e32 v5, s1
	v_mov_b32_e32 v4, s12
	v_lshl_add_u64 v[4:5], v[6:7], 2, v[4:5]
	global_load_dword v4, v[4:5], off
	v_mov_b32_e32 v6, 8
	s_waitcnt vmcnt(0) lgkmcnt(0)
	v_mul_f32_e32 v5, 0xbfb8aa3b, v4
	v_exp_f32_e32 v5, v5
	s_nop 0
	v_add_f32_e32 v5, 1.0, v5
	v_rcp_f32_e32 v5, v5
	s_nop 0
	v_mul_f32_e32 v4, v4, v5
	ds_write_b32 v18, v4 offset:18432
	s_nop 0
	v_add_u32_e32 v4, s91, v6
	ds_read_b64 v[4:5], v4
	v_add_u32_e32 v6, v8, v31
	v_ashrrev_i32_e32 v7, 31, v6
	s_waitcnt lgkmcnt(0)
	v_readfirstlane_b32 s1, v5
	v_readfirstlane_b32 s12, v4
	s_nop 0
	v_mov_b32_e32 v5, s1
	v_mov_b32_e32 v4, s12
	v_lshl_add_u64 v[4:5], v[6:7], 2, v[4:5]
	global_load_dword v4, v[4:5], off
	v_mov_b32_e32 v6, 8
	s_waitcnt vmcnt(0) lgkmcnt(0)
	v_mul_f32_e32 v5, 0xbfb8aa3b, v4
	v_exp_f32_e32 v5, v5
	s_nop 0
	v_add_f32_e32 v5, 1.0, v5
	v_rcp_f32_e32 v5, v5
	s_nop 0
	v_mul_f32_e32 v4, v4, v5
	ds_write_b32 v18, v4 offset:20480
	s_nop 0
	v_add_u32_e32 v4, s91, v6
	ds_read_b64 v[4:5], v4
	v_add_u32_e32 v6, v8, v32
	v_ashrrev_i32_e32 v7, 31, v6
	s_waitcnt lgkmcnt(0)
	v_readfirstlane_b32 s1, v5
	v_readfirstlane_b32 s12, v4
	s_nop 0
	v_mov_b32_e32 v5, s1
	v_mov_b32_e32 v4, s12
	v_lshl_add_u64 v[4:5], v[6:7], 2, v[4:5]
	global_load_dword v4, v[4:5], off
	v_mov_b32_e32 v6, 8
	s_waitcnt vmcnt(0) lgkmcnt(0)
	v_mul_f32_e32 v5, 0xbfb8aa3b, v4
	v_exp_f32_e32 v5, v5
	s_nop 0
	v_add_f32_e32 v5, 1.0, v5
	v_rcp_f32_e32 v5, v5
	s_nop 0
	v_mul_f32_e32 v4, v4, v5
	ds_write_b32 v18, v4 offset:22528
	s_nop 0
	v_add_u32_e32 v4, s91, v6
	ds_read_b64 v[4:5], v4
	v_add_u32_e32 v6, v8, v33
	v_ashrrev_i32_e32 v7, 31, v6
	s_waitcnt lgkmcnt(0)
	v_readfirstlane_b32 s1, v5
	v_readfirstlane_b32 s12, v4
	s_nop 0
	v_mov_b32_e32 v5, s1
	v_mov_b32_e32 v4, s12
	v_lshl_add_u64 v[4:5], v[6:7], 2, v[4:5]
	global_load_dword v4, v[4:5], off
	v_mov_b32_e32 v6, 8
	s_waitcnt vmcnt(0) lgkmcnt(0)
	v_mul_f32_e32 v5, 0xbfb8aa3b, v4
	v_exp_f32_e32 v5, v5
	s_nop 0
	v_add_f32_e32 v5, 1.0, v5
	v_rcp_f32_e32 v5, v5
	s_nop 0
	v_mul_f32_e32 v4, v4, v5
	ds_write_b32 v18, v4 offset:24576
	s_nop 0
	v_add_u32_e32 v4, s91, v6
	ds_read_b64 v[4:5], v4
	v_add_u32_e32 v6, v8, v34
	v_ashrrev_i32_e32 v7, 31, v6
	s_waitcnt lgkmcnt(0)
	v_readfirstlane_b32 s1, v5
	v_readfirstlane_b32 s12, v4
	s_nop 0
	v_mov_b32_e32 v5, s1
	v_mov_b32_e32 v4, s12
	v_lshl_add_u64 v[4:5], v[6:7], 2, v[4:5]
	global_load_dword v4, v[4:5], off
	v_mov_b32_e32 v6, 8
	s_waitcnt vmcnt(0) lgkmcnt(0)
	v_mul_f32_e32 v5, 0xbfb8aa3b, v4
	v_exp_f32_e32 v5, v5
	s_nop 0
	v_add_f32_e32 v5, 1.0, v5
	v_rcp_f32_e32 v5, v5
	s_nop 0
	v_mul_f32_e32 v4, v4, v5
	ds_write_b32 v18, v4 offset:26624
	s_nop 0
	v_add_u32_e32 v4, s91, v6
	ds_read_b64 v[4:5], v4
	v_add_u32_e32 v6, v8, v35
	v_ashrrev_i32_e32 v7, 31, v6
	s_waitcnt lgkmcnt(0)
	v_readfirstlane_b32 s1, v5
	v_readfirstlane_b32 s12, v4
	s_nop 0
	v_mov_b32_e32 v5, s1
	v_mov_b32_e32 v4, s12
	v_lshl_add_u64 v[4:5], v[6:7], 2, v[4:5]
	global_load_dword v4, v[4:5], off
	v_mov_b32_e32 v6, 8
	s_waitcnt vmcnt(0) lgkmcnt(0)
	v_mul_f32_e32 v5, 0xbfb8aa3b, v4
	v_exp_f32_e32 v5, v5
	s_nop 0
	v_add_f32_e32 v5, 1.0, v5
	v_rcp_f32_e32 v5, v5
	s_nop 0
	v_mul_f32_e32 v4, v4, v5
	ds_write_b32 v18, v4 offset:28672
	s_nop 0
	v_add_u32_e32 v4, s91, v6
	ds_read_b64 v[4:5], v4
	v_add_u32_e32 v6, v8, v36
	v_ashrrev_i32_e32 v7, 31, v6
	s_waitcnt lgkmcnt(0)
	v_readfirstlane_b32 s1, v5
	v_readfirstlane_b32 s12, v4
	s_nop 0
	v_mov_b32_e32 v5, s1
	s_ashr_i32 s1, s0, 31
	v_mov_b32_e32 v4, s12
	v_lshl_add_u64 v[4:5], v[6:7], 2, v[4:5]
	global_load_dword v11, v[4:5], off
	v_mov_b32_e32 v4, 0
	s_mov_b64 s[12:13], 0
	v_mov_b32_e32 v5, v4
	v_mov_b32_e32 v8, v4
	v_mov_b32_e32 v9, v4
	v_mov_b32_e32 v6, v4
	v_mov_b32_e32 v10, v4
	s_waitcnt vmcnt(0) lgkmcnt(0)
	v_mul_f32_e32 v7, 0xbfb8aa3b, v11
	v_exp_f32_e32 v13, v7
	v_mov_b32_e32 v7, v4
	v_add_f32_e32 v13, 1.0, v13
	v_rcp_f32_e32 v13, v13
	s_nop 0
	v_mul_f32_e32 v11, v11, v13
	ds_write_b32 v18, v11 offset:30720
	s_waitcnt lgkmcnt(0)
	s_barrier
	s_nop 0
	v_add_u32_e32 v11, s91, v12
	ds_read_b64 v[14:15], v11
	v_lshl_add_u32 v12, s16, 9, v17
	v_ashrrev_i32_e32 v13, 31, v12
	v_mov_b32_e32 v11, v4
	s_waitcnt lgkmcnt(0)
	v_readfirstlane_b32 s16, v14
	v_readfirstlane_b32 s17, v15
	s_add_u32 s16, s16, s20
	s_addc_u32 s17, s17, s19
	v_lshl_add_u64 v[14:15], v[12:13], 2, s[16:17]
	v_lshlrev_b32_e32 v136, 2, v12
	s_mov_b32 s100, s16
	s_mov_b32 s101, s17
	v_mov_b32_e32 v137, s18
	global_load_dword v70, v136, s[100:101]
	s_add_u32 s100, s100, 0x6000
	s_addc_u32 s101, s101, 0
	global_load_dword v72, v136, s[100:101]
	s_add_u32 s100, s100, 0x6000
	s_addc_u32 s101, s101, 0
	global_load_dword v74, v136, s[100:101]
	s_add_u32 s100, s100, 0x6000
	s_addc_u32 s101, s101, 0
	global_load_dword v76, v136, s[100:101]
	s_add_u32 s100, s100, 0x6000
	s_addc_u32 s101, s101, 0
	global_load_dword v78, v136, s[100:101]
	s_add_u32 s100, s100, 0x6000
	s_addc_u32 s101, s101, 0
	global_load_dword v80, v136, s[100:101]
	s_add_u32 s100, s100, 0x6000
	s_addc_u32 s101, s101, 0
	global_load_dword v82, v136, s[100:101]
	s_add_u32 s100, s100, 0x6000
	s_addc_u32 s101, s101, 0
	global_load_dword v84, v136, s[100:101]
	s_add_u32 s100, s100, 0x6000
	s_addc_u32 s101, s101, 0
	global_load_dword v86, v136, s[100:101]
	s_add_u32 s100, s100, 0x6000
	s_addc_u32 s101, s101, 0
	global_load_dword v88, v136, s[100:101]
	s_add_u32 s100, s100, 0x6000
	s_addc_u32 s101, s101, 0
	global_load_dword v90, v136, s[100:101]
	s_add_u32 s100, s100, 0x6000
	s_addc_u32 s101, s101, 0
	global_load_dword v92, v136, s[100:101]
	s_add_u32 s100, s100, 0x6000
	s_addc_u32 s101, s101, 0
	global_load_dword v94, v136, s[100:101]
	s_add_u32 s100, s100, 0x6000
	s_addc_u32 s101, s101, 0
	global_load_dword v96, v136, s[100:101]
	s_add_u32 s100, s100, 0x6000
	s_addc_u32 s101, s101, 0
	global_load_dword v98, v136, s[100:101]
	s_add_u32 s100, s100, 0x6000
	s_addc_u32 s101, s101, 0
	global_load_dword v100, v136, s[100:101]
	s_add_u32 s100, s100, 0x6000
	s_addc_u32 s101, s101, 0
	global_load_dword v102, v136, s[100:101]
	s_add_u32 s100, s100, 0x6000
	s_addc_u32 s101, s101, 0
	global_load_dword v104, v136, s[100:101]
	s_add_u32 s100, s100, 0x6000
	s_addc_u32 s101, s101, 0
	global_load_dword v106, v136, s[100:101]
	s_add_u32 s100, s100, 0x6000
	s_addc_u32 s101, s101, 0
	global_load_dword v108, v136, s[100:101]
	s_add_u32 s100, s100, 0x6000
	s_addc_u32 s101, s101, 0
	global_load_dword v110, v136, s[100:101]
	s_add_u32 s100, s100, 0x6000
	s_addc_u32 s101, s101, 0
	global_load_dword v112, v136, s[100:101]
	s_add_u32 s100, s100, 0x6000
	s_addc_u32 s101, s101, 0
	global_load_dword v114, v136, s[100:101]
	s_add_u32 s100, s100, 0x6000
	s_addc_u32 s101, s101, 0
	global_load_dword v116, v136, s[100:101]
	s_add_u32 s100, s100, 0x6000
	s_addc_u32 s101, s101, 0
	global_load_dword v118, v136, s[100:101]
	s_add_u32 s100, s100, 0x6000
	s_addc_u32 s101, s101, 0
	global_load_dword v120, v136, s[100:101]
	s_add_u32 s100, s100, 0x6000
	s_addc_u32 s101, s101, 0
	global_load_dword v122, v136, s[100:101]
	s_add_u32 s100, s100, 0x6000
	s_addc_u32 s101, s101, 0
	global_load_dword v124, v136, s[100:101]
	s_add_u32 s100, s100, 0x6000
	s_addc_u32 s101, s101, 0
	global_load_dword v126, v136, s[100:101]
	s_add_u32 s100, s100, 0x6000
	s_addc_u32 s101, s101, 0
	global_load_dword v128, v136, s[100:101]
	s_add_u32 s100, s100, 0x6000
	s_addc_u32 s101, s101, 0
	global_load_dword v130, v136, s[100:101]
	s_add_u32 s100, s100, 0x6000
	s_addc_u32 s101, s101, 0
	global_load_dword v132, v136, s[100:101]
	s_add_u32 s100, s100, 0x6000
	s_addc_u32 s101, s101, 0
	s_movk_i32 s12, 15
.LBB0_581:
	global_load_dword v138, v136, s[100:101]
	s_add_u32 s100, s100, 0x6000
	s_addc_u32 s101, s101, 0
	global_load_dword v140, v136, s[100:101]
	s_add_u32 s100, s100, 0x6000
	s_addc_u32 s101, s101, 0
	global_load_dword v142, v136, s[100:101]
	s_add_u32 s100, s100, 0x6000
	s_addc_u32 s101, s101, 0
	global_load_dword v144, v136, s[100:101]
	s_add_u32 s100, s100, 0x6000
	s_addc_u32 s101, s101, 0
	global_load_dword v146, v136, s[100:101]
	s_add_u32 s100, s100, 0x6000
	s_addc_u32 s101, s101, 0
	global_load_dword v148, v136, s[100:101]
	s_add_u32 s100, s100, 0x6000
	s_addc_u32 s101, s101, 0
	global_load_dword v150, v136, s[100:101]
	s_add_u32 s100, s100, 0x6000
	s_addc_u32 s101, s101, 0
	global_load_dword v152, v136, s[100:101]
	s_add_u32 s100, s100, 0x6000
	s_addc_u32 s101, s101, 0
	global_load_dword v154, v136, s[100:101]
	s_add_u32 s100, s100, 0x6000
	s_addc_u32 s101, s101, 0
	global_load_dword v156, v136, s[100:101]
	s_add_u32 s100, s100, 0x6000
	s_addc_u32 s101, s101, 0
	global_load_dword v158, v136, s[100:101]
	s_add_u32 s100, s100, 0x6000
	s_addc_u32 s101, s101, 0
	global_load_dword v166, v136, s[100:101]
	s_add_u32 s100, s100, 0x6000
	s_addc_u32 s101, s101, 0
	global_load_dword v168, v136, s[100:101]
	s_add_u32 s100, s100, 0x6000
	s_addc_u32 s101, s101, 0
	global_load_dword v170, v136, s[100:101]
	s_add_u32 s100, s100, 0x6000
	s_addc_u32 s101, s101, 0
	global_load_dword v172, v136, s[100:101]
	s_add_u32 s100, s100, 0x6000
	s_addc_u32 s101, s101, 0
	global_load_dword v174, v136, s[100:101]
	s_add_u32 s100, s100, 0x6000
	s_addc_u32 s101, s101, 0
	global_load_dword v176, v136, s[100:101]
	s_add_u32 s100, s100, 0x6000
	s_addc_u32 s101, s101, 0
	global_load_dword v178, v136, s[100:101]
	s_add_u32 s100, s100, 0x6000
	s_addc_u32 s101, s101, 0
	global_load_dword v180, v136, s[100:101]
	s_add_u32 s100, s100, 0x6000
	s_addc_u32 s101, s101, 0
	global_load_dword v182, v136, s[100:101]
	s_add_u32 s100, s100, 0x6000
	s_addc_u32 s101, s101, 0
	global_load_dword v184, v136, s[100:101]
	s_add_u32 s100, s100, 0x6000
	s_addc_u32 s101, s101, 0
	global_load_dword v186, v136, s[100:101]
	s_add_u32 s100, s100, 0x6000
	s_addc_u32 s101, s101, 0
	global_load_dword v188, v136, s[100:101]
	s_add_u32 s100, s100, 0x6000
	s_addc_u32 s101, s101, 0
	global_load_dword v190, v136, s[100:101]
	s_add_u32 s100, s100, 0x6000
	s_addc_u32 s101, s101, 0
	global_load_dword v192, v136, s[100:101]
	s_add_u32 s100, s100, 0x6000
	s_addc_u32 s101, s101, 0
	global_load_dword v194, v136, s[100:101]
	s_add_u32 s100, s100, 0x6000
	s_addc_u32 s101, s101, 0
	global_load_dword v196, v136, s[100:101]
	s_add_u32 s100, s100, 0x6000
	s_addc_u32 s101, s101, 0
	global_load_dword v198, v136, s[100:101]
	s_add_u32 s100, s100, 0x6000
	s_addc_u32 s101, s101, 0
	global_load_dword v200, v136, s[100:101]
	s_add_u32 s100, s100, 0x6000
	s_addc_u32 s101, s101, 0
	global_load_dword v202, v136, s[100:101]
	s_add_u32 s100, s100, 0x6000
	s_addc_u32 s101, s101, 0
	global_load_dword v204, v136, s[100:101]
	s_add_u32 s100, s100, 0x6000
	s_addc_u32 s101, s101, 0
	global_load_dword v206, v136, s[100:101]
	s_add_u32 s100, s100, 0x6000
	s_addc_u32 s101, s101, 0
	ds_read_b128 v[38:41], v137 offset:0
	ds_read_b128 v[42:45], v137 offset:16
	ds_read_b128 v[46:49], v137 offset:32
	ds_read_b128 v[50:53], v137 offset:48
	ds_read_b128 v[54:57], v137 offset:64
	ds_read_b128 v[58:61], v137 offset:80
	ds_read_b128 v[62:65], v137 offset:96
	ds_read_b128 v[66:69], v137 offset:112
	s_waitcnt vmcnt(60) lgkmcnt(0)
	v_pk_fma_f32 v[8:9], v[70:71], v[38:39], v[8:9] op_sel_hi:[0,1,1]
	v_pk_fma_f32 v[6:7], v[70:71], v[40:41], v[6:7] op_sel_hi:[0,1,1]
	v_pk_fma_f32 v[10:11], v[70:71], v[42:43], v[10:11] op_sel_hi:[0,1,1]
	v_pk_fma_f32 v[4:5], v[70:71], v[44:45], v[4:5] op_sel_hi:[0,1,1]
	v_pk_fma_f32 v[8:9], v[72:73], v[46:47], v[8:9] op_sel_hi:[0,1,1]
	v_pk_fma_f32 v[6:7], v[72:73], v[48:49], v[6:7] op_sel_hi:[0,1,1]
	v_pk_fma_f32 v[10:11], v[72:73], v[50:51], v[10:11] op_sel_hi:[0,1,1]
	v_pk_fma_f32 v[4:5], v[72:73], v[52:53], v[4:5] op_sel_hi:[0,1,1]
	v_pk_fma_f32 v[8:9], v[74:75], v[54:55], v[8:9] op_sel_hi:[0,1,1]
	v_pk_fma_f32 v[6:7], v[74:75], v[56:57], v[6:7] op_sel_hi:[0,1,1]
	v_pk_fma_f32 v[10:11], v[74:75], v[58:59], v[10:11] op_sel_hi:[0,1,1]
	v_pk_fma_f32 v[4:5], v[74:75], v[60:61], v[4:5] op_sel_hi:[0,1,1]
	v_pk_fma_f32 v[8:9], v[76:77], v[62:63], v[8:9] op_sel_hi:[0,1,1]
	v_pk_fma_f32 v[6:7], v[76:77], v[64:65], v[6:7] op_sel_hi:[0,1,1]
	v_pk_fma_f32 v[10:11], v[76:77], v[66:67], v[10:11] op_sel_hi:[0,1,1]
	v_pk_fma_f32 v[4:5], v[76:77], v[68:69], v[4:5] op_sel_hi:[0,1,1]
	ds_read_b128 v[38:41], v137 offset:128
	ds_read_b128 v[42:45], v137 offset:144
	ds_read_b128 v[46:49], v137 offset:160
	ds_read_b128 v[50:53], v137 offset:176
	ds_read_b128 v[54:57], v137 offset:192
	ds_read_b128 v[58:61], v137 offset:208
	ds_read_b128 v[62:65], v137 offset:224
	ds_read_b128 v[66:69], v137 offset:240
	s_waitcnt vmcnt(56) lgkmcnt(0)
	v_pk_fma_f32 v[8:9], v[78:79], v[38:39], v[8:9] op_sel_hi:[0,1,1]
	v_pk_fma_f32 v[6:7], v[78:79], v[40:41], v[6:7] op_sel_hi:[0,1,1]
	v_pk_fma_f32 v[10:11], v[78:79], v[42:43], v[10:11] op_sel_hi:[0,1,1]
	v_pk_fma_f32 v[4:5], v[78:79], v[44:45], v[4:5] op_sel_hi:[0,1,1]
	v_pk_fma_f32 v[8:9], v[80:81], v[46:47], v[8:9] op_sel_hi:[0,1,1]
	v_pk_fma_f32 v[6:7], v[80:81], v[48:49], v[6:7] op_sel_hi:[0,1,1]
	v_pk_fma_f32 v[10:11], v[80:81], v[50:51], v[10:11] op_sel_hi:[0,1,1]
	v_pk_fma_f32 v[4:5], v[80:81], v[52:53], v[4:5] op_sel_hi:[0,1,1]
	v_pk_fma_f32 v[8:9], v[82:83], v[54:55], v[8:9] op_sel_hi:[0,1,1]
	v_pk_fma_f32 v[6:7], v[82:83], v[56:57], v[6:7] op_sel_hi:[0,1,1]
	v_pk_fma_f32 v[10:11], v[82:83], v[58:59], v[10:11] op_sel_hi:[0,1,1]
	v_pk_fma_f32 v[4:5], v[82:83], v[60:61], v[4:5] op_sel_hi:[0,1,1]
	v_pk_fma_f32 v[8:9], v[84:85], v[62:63], v[8:9] op_sel_hi:[0,1,1]
	v_pk_fma_f32 v[6:7], v[84:85], v[64:65], v[6:7] op_sel_hi:[0,1,1]
	v_pk_fma_f32 v[10:11], v[84:85], v[66:67], v[10:11] op_sel_hi:[0,1,1]
	v_pk_fma_f32 v[4:5], v[84:85], v[68:69], v[4:5] op_sel_hi:[0,1,1]
	ds_read_b128 v[38:41], v137 offset:256
	ds_read_b128 v[42:45], v137 offset:272
	ds_read_b128 v[46:49], v137 offset:288
	ds_read_b128 v[50:53], v137 offset:304
	ds_read_b128 v[54:57], v137 offset:320
	ds_read_b128 v[58:61], v137 offset:336
	ds_read_b128 v[62:65], v137 offset:352
	ds_read_b128 v[66:69], v137 offset:368
	s_waitcnt vmcnt(52) lgkmcnt(0)
	v_pk_fma_f32 v[8:9], v[86:87], v[38:39], v[8:9] op_sel_hi:[0,1,1]
	v_pk_fma_f32 v[6:7], v[86:87], v[40:41], v[6:7] op_sel_hi:[0,1,1]
	v_pk_fma_f32 v[10:11], v[86:87], v[42:43], v[10:11] op_sel_hi:[0,1,1]
	v_pk_fma_f32 v[4:5], v[86:87], v[44:45], v[4:5] op_sel_hi:[0,1,1]
	v_pk_fma_f32 v[8:9], v[88:89], v[46:47], v[8:9] op_sel_hi:[0,1,1]
	v_pk_fma_f32 v[6:7], v[88:89], v[48:49], v[6:7] op_sel_hi:[0,1,1]
	v_pk_fma_f32 v[10:11], v[88:89], v[50:51], v[10:11] op_sel_hi:[0,1,1]
	v_pk_fma_f32 v[4:5], v[88:89], v[52:53], v[4:5] op_sel_hi:[0,1,1]
	v_pk_fma_f32 v[8:9], v[90:91], v[54:55], v[8:9] op_sel_hi:[0,1,1]
	v_pk_fma_f32 v[6:7], v[90:91], v[56:57], v[6:7] op_sel_hi:[0,1,1]
	v_pk_fma_f32 v[10:11], v[90:91], v[58:59], v[10:11] op_sel_hi:[0,1,1]
	v_pk_fma_f32 v[4:5], v[90:91], v[60:61], v[4:5] op_sel_hi:[0,1,1]
	v_pk_fma_f32 v[8:9], v[92:93], v[62:63], v[8:9] op_sel_hi:[0,1,1]
	v_pk_fma_f32 v[6:7], v[92:93], v[64:65], v[6:7] op_sel_hi:[0,1,1]
	v_pk_fma_f32 v[10:11], v[92:93], v[66:67], v[10:11] op_sel_hi:[0,1,1]
	v_pk_fma_f32 v[4:5], v[92:93], v[68:69], v[4:5] op_sel_hi:[0,1,1]
	ds_read_b128 v[38:41], v137 offset:384
	ds_read_b128 v[42:45], v137 offset:400
	ds_read_b128 v[46:49], v137 offset:416
	ds_read_b128 v[50:53], v137 offset:432
	ds_read_b128 v[54:57], v137 offset:448
	ds_read_b128 v[58:61], v137 offset:464
	ds_read_b128 v[62:65], v137 offset:480
	ds_read_b128 v[66:69], v137 offset:496
	s_waitcnt vmcnt(48) lgkmcnt(0)
	v_pk_fma_f32 v[8:9], v[94:95], v[38:39], v[8:9] op_sel_hi:[0,1,1]
	v_pk_fma_f32 v[6:7], v[94:95], v[40:41], v[6:7] op_sel_hi:[0,1,1]
	v_pk_fma_f32 v[10:11], v[94:95], v[42:43], v[10:11] op_sel_hi:[0,1,1]
	v_pk_fma_f32 v[4:5], v[94:95], v[44:45], v[4:5] op_sel_hi:[0,1,1]
	v_pk_fma_f32 v[8:9], v[96:97], v[46:47], v[8:9] op_sel_hi:[0,1,1]
	v_pk_fma_f32 v[6:7], v[96:97], v[48:49], v[6:7] op_sel_hi:[0,1,1]
	v_pk_fma_f32 v[10:11], v[96:97], v[50:51], v[10:11] op_sel_hi:[0,1,1]
	v_pk_fma_f32 v[4:5], v[96:97], v[52:53], v[4:5] op_sel_hi:[0,1,1]
	v_pk_fma_f32 v[8:9], v[98:99], v[54:55], v[8:9] op_sel_hi:[0,1,1]
	v_pk_fma_f32 v[6:7], v[98:99], v[56:57], v[6:7] op_sel_hi:[0,1,1]
	v_pk_fma_f32 v[10:11], v[98:99], v[58:59], v[10:11] op_sel_hi:[0,1,1]
	v_pk_fma_f32 v[4:5], v[98:99], v[60:61], v[4:5] op_sel_hi:[0,1,1]
	v_pk_fma_f32 v[8:9], v[100:101], v[62:63], v[8:9] op_sel_hi:[0,1,1]
	v_pk_fma_f32 v[6:7], v[100:101], v[64:65], v[6:7] op_sel_hi:[0,1,1]
	v_pk_fma_f32 v[10:11], v[100:101], v[66:67], v[10:11] op_sel_hi:[0,1,1]
	v_pk_fma_f32 v[4:5], v[100:101], v[68:69], v[4:5] op_sel_hi:[0,1,1]
	ds_read_b128 v[38:41], v137 offset:512
	ds_read_b128 v[42:45], v137 offset:528
	ds_read_b128 v[46:49], v137 offset:544
	ds_read_b128 v[50:53], v137 offset:560
	ds_read_b128 v[54:57], v137 offset:576
	ds_read_b128 v[58:61], v137 offset:592
	ds_read_b128 v[62:65], v137 offset:608
	ds_read_b128 v[66:69], v137 offset:624
	s_waitcnt vmcnt(44) lgkmcnt(0)
	v_pk_fma_f32 v[8:9], v[102:103], v[38:39], v[8:9] op_sel_hi:[0,1,1]
	v_pk_fma_f32 v[6:7], v[102:103], v[40:41], v[6:7] op_sel_hi:[0,1,1]
	v_pk_fma_f32 v[10:11], v[102:103], v[42:43], v[10:11] op_sel_hi:[0,1,1]
	v_pk_fma_f32 v[4:5], v[102:103], v[44:45], v[4:5] op_sel_hi:[0,1,1]
	v_pk_fma_f32 v[8:9], v[104:105], v[46:47], v[8:9] op_sel_hi:[0,1,1]
	v_pk_fma_f32 v[6:7], v[104:105], v[48:49], v[6:7] op_sel_hi:[0,1,1]
	v_pk_fma_f32 v[10:11], v[104:105], v[50:51], v[10:11] op_sel_hi:[0,1,1]
	v_pk_fma_f32 v[4:5], v[104:105], v[52:53], v[4:5] op_sel_hi:[0,1,1]
	v_pk_fma_f32 v[8:9], v[106:107], v[54:55], v[8:9] op_sel_hi:[0,1,1]
	v_pk_fma_f32 v[6:7], v[106:107], v[56:57], v[6:7] op_sel_hi:[0,1,1]
	v_pk_fma_f32 v[10:11], v[106:107], v[58:59], v[10:11] op_sel_hi:[0,1,1]
	v_pk_fma_f32 v[4:5], v[106:107], v[60:61], v[4:5] op_sel_hi:[0,1,1]
	v_pk_fma_f32 v[8:9], v[108:109], v[62:63], v[8:9] op_sel_hi:[0,1,1]
	v_pk_fma_f32 v[6:7], v[108:109], v[64:65], v[6:7] op_sel_hi:[0,1,1]
	v_pk_fma_f32 v[10:11], v[108:109], v[66:67], v[10:11] op_sel_hi:[0,1,1]
	v_pk_fma_f32 v[4:5], v[108:109], v[68:69], v[4:5] op_sel_hi:[0,1,1]
	ds_read_b128 v[38:41], v137 offset:640
	ds_read_b128 v[42:45], v137 offset:656
	ds_read_b128 v[46:49], v137 offset:672
	ds_read_b128 v[50:53], v137 offset:688
	ds_read_b128 v[54:57], v137 offset:704
	ds_read_b128 v[58:61], v137 offset:720
	ds_read_b128 v[62:65], v137 offset:736
	ds_read_b128 v[66:69], v137 offset:752
	s_waitcnt vmcnt(40) lgkmcnt(0)
	v_pk_fma_f32 v[8:9], v[110:111], v[38:39], v[8:9] op_sel_hi:[0,1,1]
	v_pk_fma_f32 v[6:7], v[110:111], v[40:41], v[6:7] op_sel_hi:[0,1,1]
	v_pk_fma_f32 v[10:11], v[110:111], v[42:43], v[10:11] op_sel_hi:[0,1,1]
	v_pk_fma_f32 v[4:5], v[110:111], v[44:45], v[4:5] op_sel_hi:[0,1,1]
	v_pk_fma_f32 v[8:9], v[112:113], v[46:47], v[8:9] op_sel_hi:[0,1,1]
	v_pk_fma_f32 v[6:7], v[112:113], v[48:49], v[6:7] op_sel_hi:[0,1,1]
	v_pk_fma_f32 v[10:11], v[112:113], v[50:51], v[10:11] op_sel_hi:[0,1,1]
	v_pk_fma_f32 v[4:5], v[112:113], v[52:53], v[4:5] op_sel_hi:[0,1,1]
	v_pk_fma_f32 v[8:9], v[114:115], v[54:55], v[8:9] op_sel_hi:[0,1,1]
	v_pk_fma_f32 v[6:7], v[114:115], v[56:57], v[6:7] op_sel_hi:[0,1,1]
	v_pk_fma_f32 v[10:11], v[114:115], v[58:59], v[10:11] op_sel_hi:[0,1,1]
	v_pk_fma_f32 v[4:5], v[114:115], v[60:61], v[4:5] op_sel_hi:[0,1,1]
	v_pk_fma_f32 v[8:9], v[116:117], v[62:63], v[8:9] op_sel_hi:[0,1,1]
	v_pk_fma_f32 v[6:7], v[116:117], v[64:65], v[6:7] op_sel_hi:[0,1,1]
	v_pk_fma_f32 v[10:11], v[116:117], v[66:67], v[10:11] op_sel_hi:[0,1,1]
	v_pk_fma_f32 v[4:5], v[116:117], v[68:69], v[4:5] op_sel_hi:[0,1,1]
	ds_read_b128 v[38:41], v137 offset:768
	ds_read_b128 v[42:45], v137 offset:784
	ds_read_b128 v[46:49], v137 offset:800
	ds_read_b128 v[50:53], v137 offset:816
	ds_read_b128 v[54:57], v137 offset:832
	ds_read_b128 v[58:61], v137 offset:848
	ds_read_b128 v[62:65], v137 offset:864
	ds_read_b128 v[66:69], v137 offset:880
	s_waitcnt vmcnt(36) lgkmcnt(0)
	v_pk_fma_f32 v[8:9], v[118:119], v[38:39], v[8:9] op_sel_hi:[0,1,1]
	v_pk_fma_f32 v[6:7], v[118:119], v[40:41], v[6:7] op_sel_hi:[0,1,1]
	v_pk_fma_f32 v[10:11], v[118:119], v[42:43], v[10:11] op_sel_hi:[0,1,1]
	v_pk_fma_f32 v[4:5], v[118:119], v[44:45], v[4:5] op_sel_hi:[0,1,1]
	v_pk_fma_f32 v[8:9], v[120:121], v[46:47], v[8:9] op_sel_hi:[0,1,1]
	v_pk_fma_f32 v[6:7], v[120:121], v[48:49], v[6:7] op_sel_hi:[0,1,1]
	v_pk_fma_f32 v[10:11], v[120:121], v[50:51], v[10:11] op_sel_hi:[0,1,1]
	v_pk_fma_f32 v[4:5], v[120:121], v[52:53], v[4:5] op_sel_hi:[0,1,1]
	v_pk_fma_f32 v[8:9], v[122:123], v[54:55], v[8:9] op_sel_hi:[0,1,1]
	v_pk_fma_f32 v[6:7], v[122:123], v[56:57], v[6:7] op_sel_hi:[0,1,1]
	v_pk_fma_f32 v[10:11], v[122:123], v[58:59], v[10:11] op_sel_hi:[0,1,1]
	v_pk_fma_f32 v[4:5], v[122:123], v[60:61], v[4:5] op_sel_hi:[0,1,1]
	v_pk_fma_f32 v[8:9], v[124:125], v[62:63], v[8:9] op_sel_hi:[0,1,1]
	v_pk_fma_f32 v[6:7], v[124:125], v[64:65], v[6:7] op_sel_hi:[0,1,1]
	v_pk_fma_f32 v[10:11], v[124:125], v[66:67], v[10:11] op_sel_hi:[0,1,1]
	v_pk_fma_f32 v[4:5], v[124:125], v[68:69], v[4:5] op_sel_hi:[0,1,1]
	ds_read_b128 v[38:41], v137 offset:896
	ds_read_b128 v[42:45], v137 offset:912
	ds_read_b128 v[46:49], v137 offset:928
	ds_read_b128 v[50:53], v137 offset:944
	ds_read_b128 v[54:57], v137 offset:960
	ds_read_b128 v[58:61], v137 offset:976
	ds_read_b128 v[62:65], v137 offset:992
	ds_read_b128 v[66:69], v137 offset:1008
	s_waitcnt vmcnt(32) lgkmcnt(0)
	v_pk_fma_f32 v[8:9], v[126:127], v[38:39], v[8:9] op_sel_hi:[0,1,1]
	v_pk_fma_f32 v[6:7], v[126:127], v[40:41], v[6:7] op_sel_hi:[0,1,1]
	v_pk_fma_f32 v[10:11], v[126:127], v[42:43], v[10:11] op_sel_hi:[0,1,1]
	v_pk_fma_f32 v[4:5], v[126:127], v[44:45], v[4:5] op_sel_hi:[0,1,1]
	v_pk_fma_f32 v[8:9], v[128:129], v[46:47], v[8:9] op_sel_hi:[0,1,1]
	v_pk_fma_f32 v[6:7], v[128:129], v[48:49], v[6:7] op_sel_hi:[0,1,1]
	v_pk_fma_f32 v[10:11], v[128:129], v[50:51], v[10:11] op_sel_hi:[0,1,1]
	v_pk_fma_f32 v[4:5], v[128:129], v[52:53], v[4:5] op_sel_hi:[0,1,1]
	v_pk_fma_f32 v[8:9], v[130:131], v[54:55], v[8:9] op_sel_hi:[0,1,1]
	v_pk_fma_f32 v[6:7], v[130:131], v[56:57], v[6:7] op_sel_hi:[0,1,1]
	v_pk_fma_f32 v[10:11], v[130:131], v[58:59], v[10:11] op_sel_hi:[0,1,1]
	v_pk_fma_f32 v[4:5], v[130:131], v[60:61], v[4:5] op_sel_hi:[0,1,1]
	v_pk_fma_f32 v[8:9], v[132:133], v[62:63], v[8:9] op_sel_hi:[0,1,1]
	v_pk_fma_f32 v[6:7], v[132:133], v[64:65], v[6:7] op_sel_hi:[0,1,1]
	v_pk_fma_f32 v[10:11], v[132:133], v[66:67], v[10:11] op_sel_hi:[0,1,1]
	v_pk_fma_f32 v[4:5], v[132:133], v[68:69], v[4:5] op_sel_hi:[0,1,1]
	v_add_u32_e32 v137, 0x400, v137
	global_load_dword v70, v136, s[100:101]
	s_add_u32 s100, s100, 0x6000
	s_addc_u32 s101, s101, 0
	global_load_dword v72, v136, s[100:101]
	s_add_u32 s100, s100, 0x6000
	s_addc_u32 s101, s101, 0
	global_load_dword v74, v136, s[100:101]
	s_add_u32 s100, s100, 0x6000
	s_addc_u32 s101, s101, 0
	global_load_dword v76, v136, s[100:101]
	s_add_u32 s100, s100, 0x6000
	s_addc_u32 s101, s101, 0
	global_load_dword v78, v136, s[100:101]
	s_add_u32 s100, s100, 0x6000
	s_addc_u32 s101, s101, 0
	global_load_dword v80, v136, s[100:101]
	s_add_u32 s100, s100, 0x6000
	s_addc_u32 s101, s101, 0
	global_load_dword v82, v136, s[100:101]
	s_add_u32 s100, s100, 0x6000
	s_addc_u32 s101, s101, 0
	global_load_dword v84, v136, s[100:101]
	s_add_u32 s100, s100, 0x6000
	s_addc_u32 s101, s101, 0
	global_load_dword v86, v136, s[100:101]
	s_add_u32 s100, s100, 0x6000
	s_addc_u32 s101, s101, 0
	global_load_dword v88, v136, s[100:101]
	s_add_u32 s100, s100, 0x6000
	s_addc_u32 s101, s101, 0
	global_load_dword v90, v136, s[100:101]
	s_add_u32 s100, s100, 0x6000
	s_addc_u32 s101, s101, 0
	global_load_dword v92, v136, s[100:101]
	s_add_u32 s100, s100, 0x6000
	s_addc_u32 s101, s101, 0
	global_load_dword v94, v136, s[100:101]
	s_add_u32 s100, s100, 0x6000
	s_addc_u32 s101, s101, 0
	global_load_dword v96, v136, s[100:101]
	s_add_u32 s100, s100, 0x6000
	s_addc_u32 s101, s101, 0
	global_load_dword v98, v136, s[100:101]
	s_add_u32 s100, s100, 0x6000
	s_addc_u32 s101, s101, 0
	global_load_dword v100, v136, s[100:101]
	s_add_u32 s100, s100, 0x6000
	s_addc_u32 s101, s101, 0
	global_load_dword v102, v136, s[100:101]
	s_add_u32 s100, s100, 0x6000
	s_addc_u32 s101, s101, 0
	global_load_dword v104, v136, s[100:101]
	s_add_u32 s100, s100, 0x6000
	s_addc_u32 s101, s101, 0
	global_load_dword v106, v136, s[100:101]
	s_add_u32 s100, s100, 0x6000
	s_addc_u32 s101, s101, 0
	global_load_dword v108, v136, s[100:101]
	s_add_u32 s100, s100, 0x6000
	s_addc_u32 s101, s101, 0
	global_load_dword v110, v136, s[100:101]
	s_add_u32 s100, s100, 0x6000
	s_addc_u32 s101, s101, 0
	global_load_dword v112, v136, s[100:101]
	s_add_u32 s100, s100, 0x6000
	s_addc_u32 s101, s101, 0
	global_load_dword v114, v136, s[100:101]
	s_add_u32 s100, s100, 0x6000
	s_addc_u32 s101, s101, 0
	global_load_dword v116, v136, s[100:101]
	s_add_u32 s100, s100, 0x6000
	s_addc_u32 s101, s101, 0
	global_load_dword v118, v136, s[100:101]
	s_add_u32 s100, s100, 0x6000
	s_addc_u32 s101, s101, 0
	global_load_dword v120, v136, s[100:101]
	s_add_u32 s100, s100, 0x6000
	s_addc_u32 s101, s101, 0
	global_load_dword v122, v136, s[100:101]
	s_add_u32 s100, s100, 0x6000
	s_addc_u32 s101, s101, 0
	global_load_dword v124, v136, s[100:101]
	s_add_u32 s100, s100, 0x6000
	s_addc_u32 s101, s101, 0
	global_load_dword v126, v136, s[100:101]
	s_add_u32 s100, s100, 0x6000
	s_addc_u32 s101, s101, 0
	global_load_dword v128, v136, s[100:101]
	s_add_u32 s100, s100, 0x6000
	s_addc_u32 s101, s101, 0
	global_load_dword v130, v136, s[100:101]
	s_add_u32 s100, s100, 0x6000
	s_addc_u32 s101, s101, 0
	global_load_dword v132, v136, s[100:101]
	s_add_u32 s100, s100, 0x6000
	s_addc_u32 s101, s101, 0
	ds_read_b128 v[38:41], v137 offset:0
	ds_read_b128 v[42:45], v137 offset:16
	ds_read_b128 v[46:49], v137 offset:32
	ds_read_b128 v[50:53], v137 offset:48
	ds_read_b128 v[54:57], v137 offset:64
	ds_read_b128 v[58:61], v137 offset:80
	ds_read_b128 v[62:65], v137 offset:96
	ds_read_b128 v[66:69], v137 offset:112
	s_waitcnt vmcnt(60) lgkmcnt(0)
	v_pk_fma_f32 v[8:9], v[138:139], v[38:39], v[8:9] op_sel_hi:[0,1,1]
	v_pk_fma_f32 v[6:7], v[138:139], v[40:41], v[6:7] op_sel_hi:[0,1,1]
	v_pk_fma_f32 v[10:11], v[138:139], v[42:43], v[10:11] op_sel_hi:[0,1,1]
	v_pk_fma_f32 v[4:5], v[138:139], v[44:45], v[4:5] op_sel_hi:[0,1,1]
	v_pk_fma_f32 v[8:9], v[140:141], v[46:47], v[8:9] op_sel_hi:[0,1,1]
	v_pk_fma_f32 v[6:7], v[140:141], v[48:49], v[6:7] op_sel_hi:[0,1,1]
	v_pk_fma_f32 v[10:11], v[140:141], v[50:51], v[10:11] op_sel_hi:[0,1,1]
	v_pk_fma_f32 v[4:5], v[140:141], v[52:53], v[4:5] op_sel_hi:[0,1,1]
	v_pk_fma_f32 v[8:9], v[142:143], v[54:55], v[8:9] op_sel_hi:[0,1,1]
	v_pk_fma_f32 v[6:7], v[142:143], v[56:57], v[6:7] op_sel_hi:[0,1,1]
	v_pk_fma_f32 v[10:11], v[142:143], v[58:59], v[10:11] op_sel_hi:[0,1,1]
	v_pk_fma_f32 v[4:5], v[142:143], v[60:61], v[4:5] op_sel_hi:[0,1,1]
	v_pk_fma_f32 v[8:9], v[144:145], v[62:63], v[8:9] op_sel_hi:[0,1,1]
	v_pk_fma_f32 v[6:7], v[144:145], v[64:65], v[6:7] op_sel_hi:[0,1,1]
	v_pk_fma_f32 v[10:11], v[144:145], v[66:67], v[10:11] op_sel_hi:[0,1,1]
	v_pk_fma_f32 v[4:5], v[144:145], v[68:69], v[4:5] op_sel_hi:[0,1,1]
	ds_read_b128 v[38:41], v137 offset:128
	ds_read_b128 v[42:45], v137 offset:144
	ds_read_b128 v[46:49], v137 offset:160
	ds_read_b128 v[50:53], v137 offset:176
	ds_read_b128 v[54:57], v137 offset:192
	ds_read_b128 v[58:61], v137 offset:208
	ds_read_b128 v[62:65], v137 offset:224
	ds_read_b128 v[66:69], v137 offset:240
	s_waitcnt vmcnt(56) lgkmcnt(0)
	v_pk_fma_f32 v[8:9], v[146:147], v[38:39], v[8:9] op_sel_hi:[0,1,1]
	v_pk_fma_f32 v[6:7], v[146:147], v[40:41], v[6:7] op_sel_hi:[0,1,1]
	v_pk_fma_f32 v[10:11], v[146:147], v[42:43], v[10:11] op_sel_hi:[0,1,1]
	v_pk_fma_f32 v[4:5], v[146:147], v[44:45], v[4:5] op_sel_hi:[0,1,1]
	v_pk_fma_f32 v[8:9], v[148:149], v[46:47], v[8:9] op_sel_hi:[0,1,1]
	v_pk_fma_f32 v[6:7], v[148:149], v[48:49], v[6:7] op_sel_hi:[0,1,1]
	v_pk_fma_f32 v[10:11], v[148:149], v[50:51], v[10:11] op_sel_hi:[0,1,1]
	v_pk_fma_f32 v[4:5], v[148:149], v[52:53], v[4:5] op_sel_hi:[0,1,1]
	v_pk_fma_f32 v[8:9], v[150:151], v[54:55], v[8:9] op_sel_hi:[0,1,1]
	v_pk_fma_f32 v[6:7], v[150:151], v[56:57], v[6:7] op_sel_hi:[0,1,1]
	v_pk_fma_f32 v[10:11], v[150:151], v[58:59], v[10:11] op_sel_hi:[0,1,1]
	v_pk_fma_f32 v[4:5], v[150:151], v[60:61], v[4:5] op_sel_hi:[0,1,1]
	v_pk_fma_f32 v[8:9], v[152:153], v[62:63], v[8:9] op_sel_hi:[0,1,1]
	v_pk_fma_f32 v[6:7], v[152:153], v[64:65], v[6:7] op_sel_hi:[0,1,1]
	v_pk_fma_f32 v[10:11], v[152:153], v[66:67], v[10:11] op_sel_hi:[0,1,1]
	v_pk_fma_f32 v[4:5], v[152:153], v[68:69], v[4:5] op_sel_hi:[0,1,1]
	ds_read_b128 v[38:41], v137 offset:256
	ds_read_b128 v[42:45], v137 offset:272
	ds_read_b128 v[46:49], v137 offset:288
	ds_read_b128 v[50:53], v137 offset:304
	ds_read_b128 v[54:57], v137 offset:320
	ds_read_b128 v[58:61], v137 offset:336
	ds_read_b128 v[62:65], v137 offset:352
	ds_read_b128 v[66:69], v137 offset:368
	s_waitcnt vmcnt(52) lgkmcnt(0)
	v_pk_fma_f32 v[8:9], v[154:155], v[38:39], v[8:9] op_sel_hi:[0,1,1]
	v_pk_fma_f32 v[6:7], v[154:155], v[40:41], v[6:7] op_sel_hi:[0,1,1]
	v_pk_fma_f32 v[10:11], v[154:155], v[42:43], v[10:11] op_sel_hi:[0,1,1]
	v_pk_fma_f32 v[4:5], v[154:155], v[44:45], v[4:5] op_sel_hi:[0,1,1]
	v_pk_fma_f32 v[8:9], v[156:157], v[46:47], v[8:9] op_sel_hi:[0,1,1]
	v_pk_fma_f32 v[6:7], v[156:157], v[48:49], v[6:7] op_sel_hi:[0,1,1]
	v_pk_fma_f32 v[10:11], v[156:157], v[50:51], v[10:11] op_sel_hi:[0,1,1]
	v_pk_fma_f32 v[4:5], v[156:157], v[52:53], v[4:5] op_sel_hi:[0,1,1]
	v_pk_fma_f32 v[8:9], v[158:159], v[54:55], v[8:9] op_sel_hi:[0,1,1]
	v_pk_fma_f32 v[6:7], v[158:159], v[56:57], v[6:7] op_sel_hi:[0,1,1]
	v_pk_fma_f32 v[10:11], v[158:159], v[58:59], v[10:11] op_sel_hi:[0,1,1]
	v_pk_fma_f32 v[4:5], v[158:159], v[60:61], v[4:5] op_sel_hi:[0,1,1]
	v_pk_fma_f32 v[8:9], v[166:167], v[62:63], v[8:9] op_sel_hi:[0,1,1]
	v_pk_fma_f32 v[6:7], v[166:167], v[64:65], v[6:7] op_sel_hi:[0,1,1]
	v_pk_fma_f32 v[10:11], v[166:167], v[66:67], v[10:11] op_sel_hi:[0,1,1]
	v_pk_fma_f32 v[4:5], v[166:167], v[68:69], v[4:5] op_sel_hi:[0,1,1]
	ds_read_b128 v[38:41], v137 offset:384
	ds_read_b128 v[42:45], v137 offset:400
	ds_read_b128 v[46:49], v137 offset:416
	ds_read_b128 v[50:53], v137 offset:432
	ds_read_b128 v[54:57], v137 offset:448
	ds_read_b128 v[58:61], v137 offset:464
	ds_read_b128 v[62:65], v137 offset:480
	ds_read_b128 v[66:69], v137 offset:496
	s_waitcnt vmcnt(48) lgkmcnt(0)
	v_pk_fma_f32 v[8:9], v[168:169], v[38:39], v[8:9] op_sel_hi:[0,1,1]
	v_pk_fma_f32 v[6:7], v[168:169], v[40:41], v[6:7] op_sel_hi:[0,1,1]
	v_pk_fma_f32 v[10:11], v[168:169], v[42:43], v[10:11] op_sel_hi:[0,1,1]
	v_pk_fma_f32 v[4:5], v[168:169], v[44:45], v[4:5] op_sel_hi:[0,1,1]
	v_pk_fma_f32 v[8:9], v[170:171], v[46:47], v[8:9] op_sel_hi:[0,1,1]
	v_pk_fma_f32 v[6:7], v[170:171], v[48:49], v[6:7] op_sel_hi:[0,1,1]
	v_pk_fma_f32 v[10:11], v[170:171], v[50:51], v[10:11] op_sel_hi:[0,1,1]
	v_pk_fma_f32 v[4:5], v[170:171], v[52:53], v[4:5] op_sel_hi:[0,1,1]
	v_pk_fma_f32 v[8:9], v[172:173], v[54:55], v[8:9] op_sel_hi:[0,1,1]
	v_pk_fma_f32 v[6:7], v[172:173], v[56:57], v[6:7] op_sel_hi:[0,1,1]
	v_pk_fma_f32 v[10:11], v[172:173], v[58:59], v[10:11] op_sel_hi:[0,1,1]
	v_pk_fma_f32 v[4:5], v[172:173], v[60:61], v[4:5] op_sel_hi:[0,1,1]
	v_pk_fma_f32 v[8:9], v[174:175], v[62:63], v[8:9] op_sel_hi:[0,1,1]
	v_pk_fma_f32 v[6:7], v[174:175], v[64:65], v[6:7] op_sel_hi:[0,1,1]
	v_pk_fma_f32 v[10:11], v[174:175], v[66:67], v[10:11] op_sel_hi:[0,1,1]
	v_pk_fma_f32 v[4:5], v[174:175], v[68:69], v[4:5] op_sel_hi:[0,1,1]
	ds_read_b128 v[38:41], v137 offset:512
	ds_read_b128 v[42:45], v137 offset:528
	ds_read_b128 v[46:49], v137 offset:544
	ds_read_b128 v[50:53], v137 offset:560
	ds_read_b128 v[54:57], v137 offset:576
	ds_read_b128 v[58:61], v137 offset:592
	ds_read_b128 v[62:65], v137 offset:608
	ds_read_b128 v[66:69], v137 offset:624
	s_waitcnt vmcnt(44) lgkmcnt(0)
	v_pk_fma_f32 v[8:9], v[176:177], v[38:39], v[8:9] op_sel_hi:[0,1,1]
	v_pk_fma_f32 v[6:7], v[176:177], v[40:41], v[6:7] op_sel_hi:[0,1,1]
	v_pk_fma_f32 v[10:11], v[176:177], v[42:43], v[10:11] op_sel_hi:[0,1,1]
	v_pk_fma_f32 v[4:5], v[176:177], v[44:45], v[4:5] op_sel_hi:[0,1,1]
	v_pk_fma_f32 v[8:9], v[178:179], v[46:47], v[8:9] op_sel_hi:[0,1,1]
	v_pk_fma_f32 v[6:7], v[178:179], v[48:49], v[6:7] op_sel_hi:[0,1,1]
	v_pk_fma_f32 v[10:11], v[178:179], v[50:51], v[10:11] op_sel_hi:[0,1,1]
	v_pk_fma_f32 v[4:5], v[178:179], v[52:53], v[4:5] op_sel_hi:[0,1,1]
	v_pk_fma_f32 v[8:9], v[180:181], v[54:55], v[8:9] op_sel_hi:[0,1,1]
	v_pk_fma_f32 v[6:7], v[180:181], v[56:57], v[6:7] op_sel_hi:[0,1,1]
	v_pk_fma_f32 v[10:11], v[180:181], v[58:59], v[10:11] op_sel_hi:[0,1,1]
	v_pk_fma_f32 v[4:5], v[180:181], v[60:61], v[4:5] op_sel_hi:[0,1,1]
	v_pk_fma_f32 v[8:9], v[182:183], v[62:63], v[8:9] op_sel_hi:[0,1,1]
	v_pk_fma_f32 v[6:7], v[182:183], v[64:65], v[6:7] op_sel_hi:[0,1,1]
	v_pk_fma_f32 v[10:11], v[182:183], v[66:67], v[10:11] op_sel_hi:[0,1,1]
	v_pk_fma_f32 v[4:5], v[182:183], v[68:69], v[4:5] op_sel_hi:[0,1,1]
	ds_read_b128 v[38:41], v137 offset:640
	ds_read_b128 v[42:45], v137 offset:656
	ds_read_b128 v[46:49], v137 offset:672
	ds_read_b128 v[50:53], v137 offset:688
	ds_read_b128 v[54:57], v137 offset:704
	ds_read_b128 v[58:61], v137 offset:720
	ds_read_b128 v[62:65], v137 offset:736
	ds_read_b128 v[66:69], v137 offset:752
	s_waitcnt vmcnt(40) lgkmcnt(0)
	v_pk_fma_f32 v[8:9], v[184:185], v[38:39], v[8:9] op_sel_hi:[0,1,1]
	v_pk_fma_f32 v[6:7], v[184:185], v[40:41], v[6:7] op_sel_hi:[0,1,1]
	v_pk_fma_f32 v[10:11], v[184:185], v[42:43], v[10:11] op_sel_hi:[0,1,1]
	v_pk_fma_f32 v[4:5], v[184:185], v[44:45], v[4:5] op_sel_hi:[0,1,1]
	v_pk_fma_f32 v[8:9], v[186:187], v[46:47], v[8:9] op_sel_hi:[0,1,1]
	v_pk_fma_f32 v[6:7], v[186:187], v[48:49], v[6:7] op_sel_hi:[0,1,1]
	v_pk_fma_f32 v[10:11], v[186:187], v[50:51], v[10:11] op_sel_hi:[0,1,1]
	v_pk_fma_f32 v[4:5], v[186:187], v[52:53], v[4:5] op_sel_hi:[0,1,1]
	v_pk_fma_f32 v[8:9], v[188:189], v[54:55], v[8:9] op_sel_hi:[0,1,1]
	v_pk_fma_f32 v[6:7], v[188:189], v[56:57], v[6:7] op_sel_hi:[0,1,1]
	v_pk_fma_f32 v[10:11], v[188:189], v[58:59], v[10:11] op_sel_hi:[0,1,1]
	v_pk_fma_f32 v[4:5], v[188:189], v[60:61], v[4:5] op_sel_hi:[0,1,1]
	v_pk_fma_f32 v[8:9], v[190:191], v[62:63], v[8:9] op_sel_hi:[0,1,1]
	v_pk_fma_f32 v[6:7], v[190:191], v[64:65], v[6:7] op_sel_hi:[0,1,1]
	v_pk_fma_f32 v[10:11], v[190:191], v[66:67], v[10:11] op_sel_hi:[0,1,1]
	v_pk_fma_f32 v[4:5], v[190:191], v[68:69], v[4:5] op_sel_hi:[0,1,1]
	ds_read_b128 v[38:41], v137 offset:768
	ds_read_b128 v[42:45], v137 offset:784
	ds_read_b128 v[46:49], v137 offset:800
	ds_read_b128 v[50:53], v137 offset:816
	ds_read_b128 v[54:57], v137 offset:832
	ds_read_b128 v[58:61], v137 offset:848
	ds_read_b128 v[62:65], v137 offset:864
	ds_read_b128 v[66:69], v137 offset:880
	s_waitcnt vmcnt(36) lgkmcnt(0)
	v_pk_fma_f32 v[8:9], v[192:193], v[38:39], v[8:9] op_sel_hi:[0,1,1]
	v_pk_fma_f32 v[6:7], v[192:193], v[40:41], v[6:7] op_sel_hi:[0,1,1]
	v_pk_fma_f32 v[10:11], v[192:193], v[42:43], v[10:11] op_sel_hi:[0,1,1]
	v_pk_fma_f32 v[4:5], v[192:193], v[44:45], v[4:5] op_sel_hi:[0,1,1]
	v_pk_fma_f32 v[8:9], v[194:195], v[46:47], v[8:9] op_sel_hi:[0,1,1]
	v_pk_fma_f32 v[6:7], v[194:195], v[48:49], v[6:7] op_sel_hi:[0,1,1]
	v_pk_fma_f32 v[10:11], v[194:195], v[50:51], v[10:11] op_sel_hi:[0,1,1]
	v_pk_fma_f32 v[4:5], v[194:195], v[52:53], v[4:5] op_sel_hi:[0,1,1]
	v_pk_fma_f32 v[8:9], v[196:197], v[54:55], v[8:9] op_sel_hi:[0,1,1]
	v_pk_fma_f32 v[6:7], v[196:197], v[56:57], v[6:7] op_sel_hi:[0,1,1]
	v_pk_fma_f32 v[10:11], v[196:197], v[58:59], v[10:11] op_sel_hi:[0,1,1]
	v_pk_fma_f32 v[4:5], v[196:197], v[60:61], v[4:5] op_sel_hi:[0,1,1]
	v_pk_fma_f32 v[8:9], v[198:199], v[62:63], v[8:9] op_sel_hi:[0,1,1]
	v_pk_fma_f32 v[6:7], v[198:199], v[64:65], v[6:7] op_sel_hi:[0,1,1]
	v_pk_fma_f32 v[10:11], v[198:199], v[66:67], v[10:11] op_sel_hi:[0,1,1]
	v_pk_fma_f32 v[4:5], v[198:199], v[68:69], v[4:5] op_sel_hi:[0,1,1]
	ds_read_b128 v[38:41], v137 offset:896
	ds_read_b128 v[42:45], v137 offset:912
	ds_read_b128 v[46:49], v137 offset:928
	ds_read_b128 v[50:53], v137 offset:944
	ds_read_b128 v[54:57], v137 offset:960
	ds_read_b128 v[58:61], v137 offset:976
	ds_read_b128 v[62:65], v137 offset:992
	ds_read_b128 v[66:69], v137 offset:1008
	s_waitcnt vmcnt(32) lgkmcnt(0)
	v_pk_fma_f32 v[8:9], v[200:201], v[38:39], v[8:9] op_sel_hi:[0,1,1]
	v_pk_fma_f32 v[6:7], v[200:201], v[40:41], v[6:7] op_sel_hi:[0,1,1]
	v_pk_fma_f32 v[10:11], v[200:201], v[42:43], v[10:11] op_sel_hi:[0,1,1]
	v_pk_fma_f32 v[4:5], v[200:201], v[44:45], v[4:5] op_sel_hi:[0,1,1]
	v_pk_fma_f32 v[8:9], v[202:203], v[46:47], v[8:9] op_sel_hi:[0,1,1]
	v_pk_fma_f32 v[6:7], v[202:203], v[48:49], v[6:7] op_sel_hi:[0,1,1]
	v_pk_fma_f32 v[10:11], v[202:203], v[50:51], v[10:11] op_sel_hi:[0,1,1]
	v_pk_fma_f32 v[4:5], v[202:203], v[52:53], v[4:5] op_sel_hi:[0,1,1]
	v_pk_fma_f32 v[8:9], v[204:205], v[54:55], v[8:9] op_sel_hi:[0,1,1]
	v_pk_fma_f32 v[6:7], v[204:205], v[56:57], v[6:7] op_sel_hi:[0,1,1]
	v_pk_fma_f32 v[10:11], v[204:205], v[58:59], v[10:11] op_sel_hi:[0,1,1]
	v_pk_fma_f32 v[4:5], v[204:205], v[60:61], v[4:5] op_sel_hi:[0,1,1]
	v_pk_fma_f32 v[8:9], v[206:207], v[62:63], v[8:9] op_sel_hi:[0,1,1]
	v_pk_fma_f32 v[6:7], v[206:207], v[64:65], v[6:7] op_sel_hi:[0,1,1]
	v_pk_fma_f32 v[10:11], v[206:207], v[66:67], v[10:11] op_sel_hi:[0,1,1]
	v_pk_fma_f32 v[4:5], v[206:207], v[68:69], v[4:5] op_sel_hi:[0,1,1]
	v_add_u32_e32 v137, 0x400, v137
	s_sub_u32 s12, s12, 1
	s_cmp_lg_u32 s12, 0
	s_cbranch_scc1 .LBB0_581
	global_load_dword v138, v136, s[100:101]
	s_add_u32 s100, s100, 0x6000
	s_addc_u32 s101, s101, 0
	global_load_dword v140, v136, s[100:101]
	s_add_u32 s100, s100, 0x6000
	s_addc_u32 s101, s101, 0
	global_load_dword v142, v136, s[100:101]
	s_add_u32 s100, s100, 0x6000
	s_addc_u32 s101, s101, 0
	global_load_dword v144, v136, s[100:101]
	s_add_u32 s100, s100, 0x6000
	s_addc_u32 s101, s101, 0
	global_load_dword v146, v136, s[100:101]
	s_add_u32 s100, s100, 0x6000
	s_addc_u32 s101, s101, 0
	global_load_dword v148, v136, s[100:101]
	s_add_u32 s100, s100, 0x6000
	s_addc_u32 s101, s101, 0
	global_load_dword v150, v136, s[100:101]
	s_add_u32 s100, s100, 0x6000
	s_addc_u32 s101, s101, 0
	global_load_dword v152, v136, s[100:101]
	s_add_u32 s100, s100, 0x6000
	s_addc_u32 s101, s101, 0
	global_load_dword v154, v136, s[100:101]
	s_add_u32 s100, s100, 0x6000
	s_addc_u32 s101, s101, 0
	global_load_dword v156, v136, s[100:101]
	s_add_u32 s100, s100, 0x6000
	s_addc_u32 s101, s101, 0
	global_load_dword v158, v136, s[100:101]
	s_add_u32 s100, s100, 0x6000
	s_addc_u32 s101, s101, 0
	global_load_dword v166, v136, s[100:101]
	s_add_u32 s100, s100, 0x6000
	s_addc_u32 s101, s101, 0
	global_load_dword v168, v136, s[100:101]
	s_add_u32 s100, s100, 0x6000
	s_addc_u32 s101, s101, 0
	global_load_dword v170, v136, s[100:101]
	s_add_u32 s100, s100, 0x6000
	s_addc_u32 s101, s101, 0
	global_load_dword v172, v136, s[100:101]
	s_add_u32 s100, s100, 0x6000
	s_addc_u32 s101, s101, 0
	global_load_dword v174, v136, s[100:101]
	s_add_u32 s100, s100, 0x6000
	s_addc_u32 s101, s101, 0
	global_load_dword v176, v136, s[100:101]
	s_add_u32 s100, s100, 0x6000
	s_addc_u32 s101, s101, 0
	global_load_dword v178, v136, s[100:101]
	s_add_u32 s100, s100, 0x6000
	s_addc_u32 s101, s101, 0
	global_load_dword v180, v136, s[100:101]
	s_add_u32 s100, s100, 0x6000
	s_addc_u32 s101, s101, 0
	global_load_dword v182, v136, s[100:101]
	s_add_u32 s100, s100, 0x6000
	s_addc_u32 s101, s101, 0
	global_load_dword v184, v136, s[100:101]
	s_add_u32 s100, s100, 0x6000
	s_addc_u32 s101, s101, 0
	global_load_dword v186, v136, s[100:101]
	s_add_u32 s100, s100, 0x6000
	s_addc_u32 s101, s101, 0
	global_load_dword v188, v136, s[100:101]
	s_add_u32 s100, s100, 0x6000
	s_addc_u32 s101, s101, 0
	global_load_dword v190, v136, s[100:101]
	s_add_u32 s100, s100, 0x6000
	s_addc_u32 s101, s101, 0
	global_load_dword v192, v136, s[100:101]
	s_add_u32 s100, s100, 0x6000
	s_addc_u32 s101, s101, 0
	global_load_dword v194, v136, s[100:101]
	s_add_u32 s100, s100, 0x6000
	s_addc_u32 s101, s101, 0
	global_load_dword v196, v136, s[100:101]
	s_add_u32 s100, s100, 0x6000
	s_addc_u32 s101, s101, 0
	global_load_dword v198, v136, s[100:101]
	s_add_u32 s100, s100, 0x6000
	s_addc_u32 s101, s101, 0
	global_load_dword v200, v136, s[100:101]
	s_add_u32 s100, s100, 0x6000
	s_addc_u32 s101, s101, 0
	global_load_dword v202, v136, s[100:101]
	s_add_u32 s100, s100, 0x6000
	s_addc_u32 s101, s101, 0
	global_load_dword v204, v136, s[100:101]
	s_add_u32 s100, s100, 0x6000
	s_addc_u32 s101, s101, 0
	global_load_dword v206, v136, s[100:101]
	s_add_u32 s100, s100, 0x6000
	s_addc_u32 s101, s101, 0
	ds_read_b128 v[38:41], v137 offset:0
	ds_read_b128 v[42:45], v137 offset:16
	ds_read_b128 v[46:49], v137 offset:32
	ds_read_b128 v[50:53], v137 offset:48
	ds_read_b128 v[54:57], v137 offset:64
	ds_read_b128 v[58:61], v137 offset:80
	ds_read_b128 v[62:65], v137 offset:96
	ds_read_b128 v[66:69], v137 offset:112
	s_waitcnt vmcnt(60) lgkmcnt(0)
	v_pk_fma_f32 v[8:9], v[70:71], v[38:39], v[8:9] op_sel_hi:[0,1,1]
	v_pk_fma_f32 v[6:7], v[70:71], v[40:41], v[6:7] op_sel_hi:[0,1,1]
	v_pk_fma_f32 v[10:11], v[70:71], v[42:43], v[10:11] op_sel_hi:[0,1,1]
	v_pk_fma_f32 v[4:5], v[70:71], v[44:45], v[4:5] op_sel_hi:[0,1,1]
	v_pk_fma_f32 v[8:9], v[72:73], v[46:47], v[8:9] op_sel_hi:[0,1,1]
	v_pk_fma_f32 v[6:7], v[72:73], v[48:49], v[6:7] op_sel_hi:[0,1,1]
	v_pk_fma_f32 v[10:11], v[72:73], v[50:51], v[10:11] op_sel_hi:[0,1,1]
	v_pk_fma_f32 v[4:5], v[72:73], v[52:53], v[4:5] op_sel_hi:[0,1,1]
	v_pk_fma_f32 v[8:9], v[74:75], v[54:55], v[8:9] op_sel_hi:[0,1,1]
	v_pk_fma_f32 v[6:7], v[74:75], v[56:57], v[6:7] op_sel_hi:[0,1,1]
	v_pk_fma_f32 v[10:11], v[74:75], v[58:59], v[10:11] op_sel_hi:[0,1,1]
	v_pk_fma_f32 v[4:5], v[74:75], v[60:61], v[4:5] op_sel_hi:[0,1,1]
	v_pk_fma_f32 v[8:9], v[76:77], v[62:63], v[8:9] op_sel_hi:[0,1,1]
	v_pk_fma_f32 v[6:7], v[76:77], v[64:65], v[6:7] op_sel_hi:[0,1,1]
	v_pk_fma_f32 v[10:11], v[76:77], v[66:67], v[10:11] op_sel_hi:[0,1,1]
	v_pk_fma_f32 v[4:5], v[76:77], v[68:69], v[4:5] op_sel_hi:[0,1,1]
	ds_read_b128 v[38:41], v137 offset:128
	ds_read_b128 v[42:45], v137 offset:144
	ds_read_b128 v[46:49], v137 offset:160
	ds_read_b128 v[50:53], v137 offset:176
	ds_read_b128 v[54:57], v137 offset:192
	ds_read_b128 v[58:61], v137 offset:208
	ds_read_b128 v[62:65], v137 offset:224
	ds_read_b128 v[66:69], v137 offset:240
	s_waitcnt vmcnt(56) lgkmcnt(0)
	v_pk_fma_f32 v[8:9], v[78:79], v[38:39], v[8:9] op_sel_hi:[0,1,1]
	v_pk_fma_f32 v[6:7], v[78:79], v[40:41], v[6:7] op_sel_hi:[0,1,1]
	v_pk_fma_f32 v[10:11], v[78:79], v[42:43], v[10:11] op_sel_hi:[0,1,1]
	v_pk_fma_f32 v[4:5], v[78:79], v[44:45], v[4:5] op_sel_hi:[0,1,1]
	v_pk_fma_f32 v[8:9], v[80:81], v[46:47], v[8:9] op_sel_hi:[0,1,1]
	v_pk_fma_f32 v[6:7], v[80:81], v[48:49], v[6:7] op_sel_hi:[0,1,1]
	v_pk_fma_f32 v[10:11], v[80:81], v[50:51], v[10:11] op_sel_hi:[0,1,1]
	v_pk_fma_f32 v[4:5], v[80:81], v[52:53], v[4:5] op_sel_hi:[0,1,1]
	v_pk_fma_f32 v[8:9], v[82:83], v[54:55], v[8:9] op_sel_hi:[0,1,1]
	v_pk_fma_f32 v[6:7], v[82:83], v[56:57], v[6:7] op_sel_hi:[0,1,1]
	v_pk_fma_f32 v[10:11], v[82:83], v[58:59], v[10:11] op_sel_hi:[0,1,1]
	v_pk_fma_f32 v[4:5], v[82:83], v[60:61], v[4:5] op_sel_hi:[0,1,1]
	v_pk_fma_f32 v[8:9], v[84:85], v[62:63], v[8:9] op_sel_hi:[0,1,1]
	v_pk_fma_f32 v[6:7], v[84:85], v[64:65], v[6:7] op_sel_hi:[0,1,1]
	v_pk_fma_f32 v[10:11], v[84:85], v[66:67], v[10:11] op_sel_hi:[0,1,1]
	v_pk_fma_f32 v[4:5], v[84:85], v[68:69], v[4:5] op_sel_hi:[0,1,1]
	ds_read_b128 v[38:41], v137 offset:256
	ds_read_b128 v[42:45], v137 offset:272
	ds_read_b128 v[46:49], v137 offset:288
	ds_read_b128 v[50:53], v137 offset:304
	ds_read_b128 v[54:57], v137 offset:320
	ds_read_b128 v[58:61], v137 offset:336
	ds_read_b128 v[62:65], v137 offset:352
	ds_read_b128 v[66:69], v137 offset:368
	s_waitcnt vmcnt(52) lgkmcnt(0)
	v_pk_fma_f32 v[8:9], v[86:87], v[38:39], v[8:9] op_sel_hi:[0,1,1]
	v_pk_fma_f32 v[6:7], v[86:87], v[40:41], v[6:7] op_sel_hi:[0,1,1]
	v_pk_fma_f32 v[10:11], v[86:87], v[42:43], v[10:11] op_sel_hi:[0,1,1]
	v_pk_fma_f32 v[4:5], v[86:87], v[44:45], v[4:5] op_sel_hi:[0,1,1]
	v_pk_fma_f32 v[8:9], v[88:89], v[46:47], v[8:9] op_sel_hi:[0,1,1]
	v_pk_fma_f32 v[6:7], v[88:89], v[48:49], v[6:7] op_sel_hi:[0,1,1]
	v_pk_fma_f32 v[10:11], v[88:89], v[50:51], v[10:11] op_sel_hi:[0,1,1]
	v_pk_fma_f32 v[4:5], v[88:89], v[52:53], v[4:5] op_sel_hi:[0,1,1]
	v_pk_fma_f32 v[8:9], v[90:91], v[54:55], v[8:9] op_sel_hi:[0,1,1]
	v_pk_fma_f32 v[6:7], v[90:91], v[56:57], v[6:7] op_sel_hi:[0,1,1]
	v_pk_fma_f32 v[10:11], v[90:91], v[58:59], v[10:11] op_sel_hi:[0,1,1]
	v_pk_fma_f32 v[4:5], v[90:91], v[60:61], v[4:5] op_sel_hi:[0,1,1]
	v_pk_fma_f32 v[8:9], v[92:93], v[62:63], v[8:9] op_sel_hi:[0,1,1]
	v_pk_fma_f32 v[6:7], v[92:93], v[64:65], v[6:7] op_sel_hi:[0,1,1]
	v_pk_fma_f32 v[10:11], v[92:93], v[66:67], v[10:11] op_sel_hi:[0,1,1]
	v_pk_fma_f32 v[4:5], v[92:93], v[68:69], v[4:5] op_sel_hi:[0,1,1]
	ds_read_b128 v[38:41], v137 offset:384
	ds_read_b128 v[42:45], v137 offset:400
	ds_read_b128 v[46:49], v137 offset:416
	ds_read_b128 v[50:53], v137 offset:432
	ds_read_b128 v[54:57], v137 offset:448
	ds_read_b128 v[58:61], v137 offset:464
	ds_read_b128 v[62:65], v137 offset:480
	ds_read_b128 v[66:69], v137 offset:496
	s_waitcnt vmcnt(48) lgkmcnt(0)
	v_pk_fma_f32 v[8:9], v[94:95], v[38:39], v[8:9] op_sel_hi:[0,1,1]
	v_pk_fma_f32 v[6:7], v[94:95], v[40:41], v[6:7] op_sel_hi:[0,1,1]
	v_pk_fma_f32 v[10:11], v[94:95], v[42:43], v[10:11] op_sel_hi:[0,1,1]
	v_pk_fma_f32 v[4:5], v[94:95], v[44:45], v[4:5] op_sel_hi:[0,1,1]
	v_pk_fma_f32 v[8:9], v[96:97], v[46:47], v[8:9] op_sel_hi:[0,1,1]
	v_pk_fma_f32 v[6:7], v[96:97], v[48:49], v[6:7] op_sel_hi:[0,1,1]
	v_pk_fma_f32 v[10:11], v[96:97], v[50:51], v[10:11] op_sel_hi:[0,1,1]
	v_pk_fma_f32 v[4:5], v[96:97], v[52:53], v[4:5] op_sel_hi:[0,1,1]
	v_pk_fma_f32 v[8:9], v[98:99], v[54:55], v[8:9] op_sel_hi:[0,1,1]
	v_pk_fma_f32 v[6:7], v[98:99], v[56:57], v[6:7] op_sel_hi:[0,1,1]
	v_pk_fma_f32 v[10:11], v[98:99], v[58:59], v[10:11] op_sel_hi:[0,1,1]
	v_pk_fma_f32 v[4:5], v[98:99], v[60:61], v[4:5] op_sel_hi:[0,1,1]
	v_pk_fma_f32 v[8:9], v[100:101], v[62:63], v[8:9] op_sel_hi:[0,1,1]
	v_pk_fma_f32 v[6:7], v[100:101], v[64:65], v[6:7] op_sel_hi:[0,1,1]
	v_pk_fma_f32 v[10:11], v[100:101], v[66:67], v[10:11] op_sel_hi:[0,1,1]
	v_pk_fma_f32 v[4:5], v[100:101], v[68:69], v[4:5] op_sel_hi:[0,1,1]
	ds_read_b128 v[38:41], v137 offset:512
	ds_read_b128 v[42:45], v137 offset:528
	ds_read_b128 v[46:49], v137 offset:544
	ds_read_b128 v[50:53], v137 offset:560
	ds_read_b128 v[54:57], v137 offset:576
	ds_read_b128 v[58:61], v137 offset:592
	ds_read_b128 v[62:65], v137 offset:608
	ds_read_b128 v[66:69], v137 offset:624
	s_waitcnt vmcnt(44) lgkmcnt(0)
	v_pk_fma_f32 v[8:9], v[102:103], v[38:39], v[8:9] op_sel_hi:[0,1,1]
	v_pk_fma_f32 v[6:7], v[102:103], v[40:41], v[6:7] op_sel_hi:[0,1,1]
	v_pk_fma_f32 v[10:11], v[102:103], v[42:43], v[10:11] op_sel_hi:[0,1,1]
	v_pk_fma_f32 v[4:5], v[102:103], v[44:45], v[4:5] op_sel_hi:[0,1,1]
	v_pk_fma_f32 v[8:9], v[104:105], v[46:47], v[8:9] op_sel_hi:[0,1,1]
	v_pk_fma_f32 v[6:7], v[104:105], v[48:49], v[6:7] op_sel_hi:[0,1,1]
	v_pk_fma_f32 v[10:11], v[104:105], v[50:51], v[10:11] op_sel_hi:[0,1,1]
	v_pk_fma_f32 v[4:5], v[104:105], v[52:53], v[4:5] op_sel_hi:[0,1,1]
	v_pk_fma_f32 v[8:9], v[106:107], v[54:55], v[8:9] op_sel_hi:[0,1,1]
	v_pk_fma_f32 v[6:7], v[106:107], v[56:57], v[6:7] op_sel_hi:[0,1,1]
	v_pk_fma_f32 v[10:11], v[106:107], v[58:59], v[10:11] op_sel_hi:[0,1,1]
	v_pk_fma_f32 v[4:5], v[106:107], v[60:61], v[4:5] op_sel_hi:[0,1,1]
	v_pk_fma_f32 v[8:9], v[108:109], v[62:63], v[8:9] op_sel_hi:[0,1,1]
	v_pk_fma_f32 v[6:7], v[108:109], v[64:65], v[6:7] op_sel_hi:[0,1,1]
	v_pk_fma_f32 v[10:11], v[108:109], v[66:67], v[10:11] op_sel_hi:[0,1,1]
	v_pk_fma_f32 v[4:5], v[108:109], v[68:69], v[4:5] op_sel_hi:[0,1,1]
	ds_read_b128 v[38:41], v137 offset:640
	ds_read_b128 v[42:45], v137 offset:656
	ds_read_b128 v[46:49], v137 offset:672
	ds_read_b128 v[50:53], v137 offset:688
	ds_read_b128 v[54:57], v137 offset:704
	ds_read_b128 v[58:61], v137 offset:720
	ds_read_b128 v[62:65], v137 offset:736
	ds_read_b128 v[66:69], v137 offset:752
	s_waitcnt vmcnt(40) lgkmcnt(0)
	v_pk_fma_f32 v[8:9], v[110:111], v[38:39], v[8:9] op_sel_hi:[0,1,1]
	v_pk_fma_f32 v[6:7], v[110:111], v[40:41], v[6:7] op_sel_hi:[0,1,1]
	v_pk_fma_f32 v[10:11], v[110:111], v[42:43], v[10:11] op_sel_hi:[0,1,1]
	v_pk_fma_f32 v[4:5], v[110:111], v[44:45], v[4:5] op_sel_hi:[0,1,1]
	v_pk_fma_f32 v[8:9], v[112:113], v[46:47], v[8:9] op_sel_hi:[0,1,1]
	v_pk_fma_f32 v[6:7], v[112:113], v[48:49], v[6:7] op_sel_hi:[0,1,1]
	v_pk_fma_f32 v[10:11], v[112:113], v[50:51], v[10:11] op_sel_hi:[0,1,1]
	v_pk_fma_f32 v[4:5], v[112:113], v[52:53], v[4:5] op_sel_hi:[0,1,1]
	v_pk_fma_f32 v[8:9], v[114:115], v[54:55], v[8:9] op_sel_hi:[0,1,1]
	v_pk_fma_f32 v[6:7], v[114:115], v[56:57], v[6:7] op_sel_hi:[0,1,1]
	v_pk_fma_f32 v[10:11], v[114:115], v[58:59], v[10:11] op_sel_hi:[0,1,1]
	v_pk_fma_f32 v[4:5], v[114:115], v[60:61], v[4:5] op_sel_hi:[0,1,1]
	v_pk_fma_f32 v[8:9], v[116:117], v[62:63], v[8:9] op_sel_hi:[0,1,1]
	v_pk_fma_f32 v[6:7], v[116:117], v[64:65], v[6:7] op_sel_hi:[0,1,1]
	v_pk_fma_f32 v[10:11], v[116:117], v[66:67], v[10:11] op_sel_hi:[0,1,1]
	v_pk_fma_f32 v[4:5], v[116:117], v[68:69], v[4:5] op_sel_hi:[0,1,1]
	ds_read_b128 v[38:41], v137 offset:768
	ds_read_b128 v[42:45], v137 offset:784
	ds_read_b128 v[46:49], v137 offset:800
	ds_read_b128 v[50:53], v137 offset:816
	ds_read_b128 v[54:57], v137 offset:832
	ds_read_b128 v[58:61], v137 offset:848
	ds_read_b128 v[62:65], v137 offset:864
	ds_read_b128 v[66:69], v137 offset:880
	s_waitcnt vmcnt(36) lgkmcnt(0)
	v_pk_fma_f32 v[8:9], v[118:119], v[38:39], v[8:9] op_sel_hi:[0,1,1]
	v_pk_fma_f32 v[6:7], v[118:119], v[40:41], v[6:7] op_sel_hi:[0,1,1]
	v_pk_fma_f32 v[10:11], v[118:119], v[42:43], v[10:11] op_sel_hi:[0,1,1]
	v_pk_fma_f32 v[4:5], v[118:119], v[44:45], v[4:5] op_sel_hi:[0,1,1]
	v_pk_fma_f32 v[8:9], v[120:121], v[46:47], v[8:9] op_sel_hi:[0,1,1]
	v_pk_fma_f32 v[6:7], v[120:121], v[48:49], v[6:7] op_sel_hi:[0,1,1]
	v_pk_fma_f32 v[10:11], v[120:121], v[50:51], v[10:11] op_sel_hi:[0,1,1]
	v_pk_fma_f32 v[4:5], v[120:121], v[52:53], v[4:5] op_sel_hi:[0,1,1]
	v_pk_fma_f32 v[8:9], v[122:123], v[54:55], v[8:9] op_sel_hi:[0,1,1]
	v_pk_fma_f32 v[6:7], v[122:123], v[56:57], v[6:7] op_sel_hi:[0,1,1]
	v_pk_fma_f32 v[10:11], v[122:123], v[58:59], v[10:11] op_sel_hi:[0,1,1]
	v_pk_fma_f32 v[4:5], v[122:123], v[60:61], v[4:5] op_sel_hi:[0,1,1]
	v_pk_fma_f32 v[8:9], v[124:125], v[62:63], v[8:9] op_sel_hi:[0,1,1]
	v_pk_fma_f32 v[6:7], v[124:125], v[64:65], v[6:7] op_sel_hi:[0,1,1]
	v_pk_fma_f32 v[10:11], v[124:125], v[66:67], v[10:11] op_sel_hi:[0,1,1]
	v_pk_fma_f32 v[4:5], v[124:125], v[68:69], v[4:5] op_sel_hi:[0,1,1]
	ds_read_b128 v[38:41], v137 offset:896
	ds_read_b128 v[42:45], v137 offset:912
	ds_read_b128 v[46:49], v137 offset:928
	ds_read_b128 v[50:53], v137 offset:944
	ds_read_b128 v[54:57], v137 offset:960
	ds_read_b128 v[58:61], v137 offset:976
	ds_read_b128 v[62:65], v137 offset:992
	ds_read_b128 v[66:69], v137 offset:1008
	s_waitcnt vmcnt(32) lgkmcnt(0)
	v_pk_fma_f32 v[8:9], v[126:127], v[38:39], v[8:9] op_sel_hi:[0,1,1]
	v_pk_fma_f32 v[6:7], v[126:127], v[40:41], v[6:7] op_sel_hi:[0,1,1]
	v_pk_fma_f32 v[10:11], v[126:127], v[42:43], v[10:11] op_sel_hi:[0,1,1]
	v_pk_fma_f32 v[4:5], v[126:127], v[44:45], v[4:5] op_sel_hi:[0,1,1]
	v_pk_fma_f32 v[8:9], v[128:129], v[46:47], v[8:9] op_sel_hi:[0,1,1]
	v_pk_fma_f32 v[6:7], v[128:129], v[48:49], v[6:7] op_sel_hi:[0,1,1]
	v_pk_fma_f32 v[10:11], v[128:129], v[50:51], v[10:11] op_sel_hi:[0,1,1]
	v_pk_fma_f32 v[4:5], v[128:129], v[52:53], v[4:5] op_sel_hi:[0,1,1]
	v_pk_fma_f32 v[8:9], v[130:131], v[54:55], v[8:9] op_sel_hi:[0,1,1]
	v_pk_fma_f32 v[6:7], v[130:131], v[56:57], v[6:7] op_sel_hi:[0,1,1]
	v_pk_fma_f32 v[10:11], v[130:131], v[58:59], v[10:11] op_sel_hi:[0,1,1]
	v_pk_fma_f32 v[4:5], v[130:131], v[60:61], v[4:5] op_sel_hi:[0,1,1]
	v_pk_fma_f32 v[8:9], v[132:133], v[62:63], v[8:9] op_sel_hi:[0,1,1]
	v_pk_fma_f32 v[6:7], v[132:133], v[64:65], v[6:7] op_sel_hi:[0,1,1]
	v_pk_fma_f32 v[10:11], v[132:133], v[66:67], v[10:11] op_sel_hi:[0,1,1]
	v_pk_fma_f32 v[4:5], v[132:133], v[68:69], v[4:5] op_sel_hi:[0,1,1]
	v_add_u32_e32 v137, 0x400, v137
	ds_read_b128 v[38:41], v137 offset:0
	ds_read_b128 v[42:45], v137 offset:16
	ds_read_b128 v[46:49], v137 offset:32
	ds_read_b128 v[50:53], v137 offset:48
	ds_read_b128 v[54:57], v137 offset:64
	ds_read_b128 v[58:61], v137 offset:80
	ds_read_b128 v[62:65], v137 offset:96
	ds_read_b128 v[66:69], v137 offset:112
	s_waitcnt vmcnt(28) lgkmcnt(0)
	v_pk_fma_f32 v[8:9], v[138:139], v[38:39], v[8:9] op_sel_hi:[0,1,1]
	v_pk_fma_f32 v[6:7], v[138:139], v[40:41], v[6:7] op_sel_hi:[0,1,1]
	v_pk_fma_f32 v[10:11], v[138:139], v[42:43], v[10:11] op_sel_hi:[0,1,1]
	v_pk_fma_f32 v[4:5], v[138:139], v[44:45], v[4:5] op_sel_hi:[0,1,1]
	v_pk_fma_f32 v[8:9], v[140:141], v[46:47], v[8:9] op_sel_hi:[0,1,1]
	v_pk_fma_f32 v[6:7], v[140:141], v[48:49], v[6:7] op_sel_hi:[0,1,1]
	v_pk_fma_f32 v[10:11], v[140:141], v[50:51], v[10:11] op_sel_hi:[0,1,1]
	v_pk_fma_f32 v[4:5], v[140:141], v[52:53], v[4:5] op_sel_hi:[0,1,1]
	v_pk_fma_f32 v[8:9], v[142:143], v[54:55], v[8:9] op_sel_hi:[0,1,1]
	v_pk_fma_f32 v[6:7], v[142:143], v[56:57], v[6:7] op_sel_hi:[0,1,1]
	v_pk_fma_f32 v[10:11], v[142:143], v[58:59], v[10:11] op_sel_hi:[0,1,1]
	v_pk_fma_f32 v[4:5], v[142:143], v[60:61], v[4:5] op_sel_hi:[0,1,1]
	v_pk_fma_f32 v[8:9], v[144:145], v[62:63], v[8:9] op_sel_hi:[0,1,1]
	v_pk_fma_f32 v[6:7], v[144:145], v[64:65], v[6:7] op_sel_hi:[0,1,1]
	v_pk_fma_f32 v[10:11], v[144:145], v[66:67], v[10:11] op_sel_hi:[0,1,1]
	v_pk_fma_f32 v[4:5], v[144:145], v[68:69], v[4:5] op_sel_hi:[0,1,1]
	ds_read_b128 v[38:41], v137 offset:128
	ds_read_b128 v[42:45], v137 offset:144
	ds_read_b128 v[46:49], v137 offset:160
	ds_read_b128 v[50:53], v137 offset:176
	ds_read_b128 v[54:57], v137 offset:192
	ds_read_b128 v[58:61], v137 offset:208
	ds_read_b128 v[62:65], v137 offset:224
	ds_read_b128 v[66:69], v137 offset:240
	s_waitcnt vmcnt(24) lgkmcnt(0)
	v_pk_fma_f32 v[8:9], v[146:147], v[38:39], v[8:9] op_sel_hi:[0,1,1]
	v_pk_fma_f32 v[6:7], v[146:147], v[40:41], v[6:7] op_sel_hi:[0,1,1]
	v_pk_fma_f32 v[10:11], v[146:147], v[42:43], v[10:11] op_sel_hi:[0,1,1]
	v_pk_fma_f32 v[4:5], v[146:147], v[44:45], v[4:5] op_sel_hi:[0,1,1]
	v_pk_fma_f32 v[8:9], v[148:149], v[46:47], v[8:9] op_sel_hi:[0,1,1]
	v_pk_fma_f32 v[6:7], v[148:149], v[48:49], v[6:7] op_sel_hi:[0,1,1]
	v_pk_fma_f32 v[10:11], v[148:149], v[50:51], v[10:11] op_sel_hi:[0,1,1]
	v_pk_fma_f32 v[4:5], v[148:149], v[52:53], v[4:5] op_sel_hi:[0,1,1]
	v_pk_fma_f32 v[8:9], v[150:151], v[54:55], v[8:9] op_sel_hi:[0,1,1]
	v_pk_fma_f32 v[6:7], v[150:151], v[56:57], v[6:7] op_sel_hi:[0,1,1]
	v_pk_fma_f32 v[10:11], v[150:151], v[58:59], v[10:11] op_sel_hi:[0,1,1]
	v_pk_fma_f32 v[4:5], v[150:151], v[60:61], v[4:5] op_sel_hi:[0,1,1]
	v_pk_fma_f32 v[8:9], v[152:153], v[62:63], v[8:9] op_sel_hi:[0,1,1]
	v_pk_fma_f32 v[6:7], v[152:153], v[64:65], v[6:7] op_sel_hi:[0,1,1]
	v_pk_fma_f32 v[10:11], v[152:153], v[66:67], v[10:11] op_sel_hi:[0,1,1]
	v_pk_fma_f32 v[4:5], v[152:153], v[68:69], v[4:5] op_sel_hi:[0,1,1]
	ds_read_b128 v[38:41], v137 offset:256
	ds_read_b128 v[42:45], v137 offset:272
	ds_read_b128 v[46:49], v137 offset:288
	ds_read_b128 v[50:53], v137 offset:304
	ds_read_b128 v[54:57], v137 offset:320
	ds_read_b128 v[58:61], v137 offset:336
	ds_read_b128 v[62:65], v137 offset:352
	ds_read_b128 v[66:69], v137 offset:368
	s_waitcnt vmcnt(20) lgkmcnt(0)
	v_pk_fma_f32 v[8:9], v[154:155], v[38:39], v[8:9] op_sel_hi:[0,1,1]
	v_pk_fma_f32 v[6:7], v[154:155], v[40:41], v[6:7] op_sel_hi:[0,1,1]
	v_pk_fma_f32 v[10:11], v[154:155], v[42:43], v[10:11] op_sel_hi:[0,1,1]
	v_pk_fma_f32 v[4:5], v[154:155], v[44:45], v[4:5] op_sel_hi:[0,1,1]
	v_pk_fma_f32 v[8:9], v[156:157], v[46:47], v[8:9] op_sel_hi:[0,1,1]
	v_pk_fma_f32 v[6:7], v[156:157], v[48:49], v[6:7] op_sel_hi:[0,1,1]
	v_pk_fma_f32 v[10:11], v[156:157], v[50:51], v[10:11] op_sel_hi:[0,1,1]
	v_pk_fma_f32 v[4:5], v[156:157], v[52:53], v[4:5] op_sel_hi:[0,1,1]
	v_pk_fma_f32 v[8:9], v[158:159], v[54:55], v[8:9] op_sel_hi:[0,1,1]
	v_pk_fma_f32 v[6:7], v[158:159], v[56:57], v[6:7] op_sel_hi:[0,1,1]
	v_pk_fma_f32 v[10:11], v[158:159], v[58:59], v[10:11] op_sel_hi:[0,1,1]
	v_pk_fma_f32 v[4:5], v[158:159], v[60:61], v[4:5] op_sel_hi:[0,1,1]
	v_pk_fma_f32 v[8:9], v[166:167], v[62:63], v[8:9] op_sel_hi:[0,1,1]
	v_pk_fma_f32 v[6:7], v[166:167], v[64:65], v[6:7] op_sel_hi:[0,1,1]
	v_pk_fma_f32 v[10:11], v[166:167], v[66:67], v[10:11] op_sel_hi:[0,1,1]
	v_pk_fma_f32 v[4:5], v[166:167], v[68:69], v[4:5] op_sel_hi:[0,1,1]
	ds_read_b128 v[38:41], v137 offset:384
	ds_read_b128 v[42:45], v137 offset:400
	ds_read_b128 v[46:49], v137 offset:416
	ds_read_b128 v[50:53], v137 offset:432
	ds_read_b128 v[54:57], v137 offset:448
	ds_read_b128 v[58:61], v137 offset:464
	ds_read_b128 v[62:65], v137 offset:480
	ds_read_b128 v[66:69], v137 offset:496
	s_waitcnt vmcnt(16) lgkmcnt(0)
	v_pk_fma_f32 v[8:9], v[168:169], v[38:39], v[8:9] op_sel_hi:[0,1,1]
	v_pk_fma_f32 v[6:7], v[168:169], v[40:41], v[6:7] op_sel_hi:[0,1,1]
	v_pk_fma_f32 v[10:11], v[168:169], v[42:43], v[10:11] op_sel_hi:[0,1,1]
	v_pk_fma_f32 v[4:5], v[168:169], v[44:45], v[4:5] op_sel_hi:[0,1,1]
	v_pk_fma_f32 v[8:9], v[170:171], v[46:47], v[8:9] op_sel_hi:[0,1,1]
	v_pk_fma_f32 v[6:7], v[170:171], v[48:49], v[6:7] op_sel_hi:[0,1,1]
	v_pk_fma_f32 v[10:11], v[170:171], v[50:51], v[10:11] op_sel_hi:[0,1,1]
	v_pk_fma_f32 v[4:5], v[170:171], v[52:53], v[4:5] op_sel_hi:[0,1,1]
	v_pk_fma_f32 v[8:9], v[172:173], v[54:55], v[8:9] op_sel_hi:[0,1,1]
	v_pk_fma_f32 v[6:7], v[172:173], v[56:57], v[6:7] op_sel_hi:[0,1,1]
	v_pk_fma_f32 v[10:11], v[172:173], v[58:59], v[10:11] op_sel_hi:[0,1,1]
	v_pk_fma_f32 v[4:5], v[172:173], v[60:61], v[4:5] op_sel_hi:[0,1,1]
	v_pk_fma_f32 v[8:9], v[174:175], v[62:63], v[8:9] op_sel_hi:[0,1,1]
	v_pk_fma_f32 v[6:7], v[174:175], v[64:65], v[6:7] op_sel_hi:[0,1,1]
	v_pk_fma_f32 v[10:11], v[174:175], v[66:67], v[10:11] op_sel_hi:[0,1,1]
	v_pk_fma_f32 v[4:5], v[174:175], v[68:69], v[4:5] op_sel_hi:[0,1,1]
	ds_read_b128 v[38:41], v137 offset:512
	ds_read_b128 v[42:45], v137 offset:528
	ds_read_b128 v[46:49], v137 offset:544
	ds_read_b128 v[50:53], v137 offset:560
	ds_read_b128 v[54:57], v137 offset:576
	ds_read_b128 v[58:61], v137 offset:592
	ds_read_b128 v[62:65], v137 offset:608
	ds_read_b128 v[66:69], v137 offset:624
	s_waitcnt vmcnt(12) lgkmcnt(0)
	v_pk_fma_f32 v[8:9], v[176:177], v[38:39], v[8:9] op_sel_hi:[0,1,1]
	v_pk_fma_f32 v[6:7], v[176:177], v[40:41], v[6:7] op_sel_hi:[0,1,1]
	v_pk_fma_f32 v[10:11], v[176:177], v[42:43], v[10:11] op_sel_hi:[0,1,1]
	v_pk_fma_f32 v[4:5], v[176:177], v[44:45], v[4:5] op_sel_hi:[0,1,1]
	v_pk_fma_f32 v[8:9], v[178:179], v[46:47], v[8:9] op_sel_hi:[0,1,1]
	v_pk_fma_f32 v[6:7], v[178:179], v[48:49], v[6:7] op_sel_hi:[0,1,1]
	v_pk_fma_f32 v[10:11], v[178:179], v[50:51], v[10:11] op_sel_hi:[0,1,1]
	v_pk_fma_f32 v[4:5], v[178:179], v[52:53], v[4:5] op_sel_hi:[0,1,1]
	v_pk_fma_f32 v[8:9], v[180:181], v[54:55], v[8:9] op_sel_hi:[0,1,1]
	v_pk_fma_f32 v[6:7], v[180:181], v[56:57], v[6:7] op_sel_hi:[0,1,1]
	v_pk_fma_f32 v[10:11], v[180:181], v[58:59], v[10:11] op_sel_hi:[0,1,1]
	v_pk_fma_f32 v[4:5], v[180:181], v[60:61], v[4:5] op_sel_hi:[0,1,1]
	v_pk_fma_f32 v[8:9], v[182:183], v[62:63], v[8:9] op_sel_hi:[0,1,1]
	v_pk_fma_f32 v[6:7], v[182:183], v[64:65], v[6:7] op_sel_hi:[0,1,1]
	v_pk_fma_f32 v[10:11], v[182:183], v[66:67], v[10:11] op_sel_hi:[0,1,1]
	v_pk_fma_f32 v[4:5], v[182:183], v[68:69], v[4:5] op_sel_hi:[0,1,1]
	ds_read_b128 v[38:41], v137 offset:640
	ds_read_b128 v[42:45], v137 offset:656
	ds_read_b128 v[46:49], v137 offset:672
	ds_read_b128 v[50:53], v137 offset:688
	ds_read_b128 v[54:57], v137 offset:704
	ds_read_b128 v[58:61], v137 offset:720
	ds_read_b128 v[62:65], v137 offset:736
	ds_read_b128 v[66:69], v137 offset:752
	s_waitcnt vmcnt(8) lgkmcnt(0)
	v_pk_fma_f32 v[8:9], v[184:185], v[38:39], v[8:9] op_sel_hi:[0,1,1]
	v_pk_fma_f32 v[6:7], v[184:185], v[40:41], v[6:7] op_sel_hi:[0,1,1]
	v_pk_fma_f32 v[10:11], v[184:185], v[42:43], v[10:11] op_sel_hi:[0,1,1]
	v_pk_fma_f32 v[4:5], v[184:185], v[44:45], v[4:5] op_sel_hi:[0,1,1]
	v_pk_fma_f32 v[8:9], v[186:187], v[46:47], v[8:9] op_sel_hi:[0,1,1]
	v_pk_fma_f32 v[6:7], v[186:187], v[48:49], v[6:7] op_sel_hi:[0,1,1]
	v_pk_fma_f32 v[10:11], v[186:187], v[50:51], v[10:11] op_sel_hi:[0,1,1]
	v_pk_fma_f32 v[4:5], v[186:187], v[52:53], v[4:5] op_sel_hi:[0,1,1]
	v_pk_fma_f32 v[8:9], v[188:189], v[54:55], v[8:9] op_sel_hi:[0,1,1]
	v_pk_fma_f32 v[6:7], v[188:189], v[56:57], v[6:7] op_sel_hi:[0,1,1]
	v_pk_fma_f32 v[10:11], v[188:189], v[58:59], v[10:11] op_sel_hi:[0,1,1]
	v_pk_fma_f32 v[4:5], v[188:189], v[60:61], v[4:5] op_sel_hi:[0,1,1]
	v_pk_fma_f32 v[8:9], v[190:191], v[62:63], v[8:9] op_sel_hi:[0,1,1]
	v_pk_fma_f32 v[6:7], v[190:191], v[64:65], v[6:7] op_sel_hi:[0,1,1]
	v_pk_fma_f32 v[10:11], v[190:191], v[66:67], v[10:11] op_sel_hi:[0,1,1]
	v_pk_fma_f32 v[4:5], v[190:191], v[68:69], v[4:5] op_sel_hi:[0,1,1]
	ds_read_b128 v[38:41], v137 offset:768
	ds_read_b128 v[42:45], v137 offset:784
	ds_read_b128 v[46:49], v137 offset:800
	ds_read_b128 v[50:53], v137 offset:816
	ds_read_b128 v[54:57], v137 offset:832
	ds_read_b128 v[58:61], v137 offset:848
	ds_read_b128 v[62:65], v137 offset:864
	ds_read_b128 v[66:69], v137 offset:880
	s_waitcnt vmcnt(4) lgkmcnt(0)
	v_pk_fma_f32 v[8:9], v[192:193], v[38:39], v[8:9] op_sel_hi:[0,1,1]
	v_pk_fma_f32 v[6:7], v[192:193], v[40:41], v[6:7] op_sel_hi:[0,1,1]
	v_pk_fma_f32 v[10:11], v[192:193], v[42:43], v[10:11] op_sel_hi:[0,1,1]
	v_pk_fma_f32 v[4:5], v[192:193], v[44:45], v[4:5] op_sel_hi:[0,1,1]
	v_pk_fma_f32 v[8:9], v[194:195], v[46:47], v[8:9] op_sel_hi:[0,1,1]
	v_pk_fma_f32 v[6:7], v[194:195], v[48:49], v[6:7] op_sel_hi:[0,1,1]
	v_pk_fma_f32 v[10:11], v[194:195], v[50:51], v[10:11] op_sel_hi:[0,1,1]
	v_pk_fma_f32 v[4:5], v[194:195], v[52:53], v[4:5] op_sel_hi:[0,1,1]
	v_pk_fma_f32 v[8:9], v[196:197], v[54:55], v[8:9] op_sel_hi:[0,1,1]
	v_pk_fma_f32 v[6:7], v[196:197], v[56:57], v[6:7] op_sel_hi:[0,1,1]
	v_pk_fma_f32 v[10:11], v[196:197], v[58:59], v[10:11] op_sel_hi:[0,1,1]
	v_pk_fma_f32 v[4:5], v[196:197], v[60:61], v[4:5] op_sel_hi:[0,1,1]
	v_pk_fma_f32 v[8:9], v[198:199], v[62:63], v[8:9] op_sel_hi:[0,1,1]
	v_pk_fma_f32 v[6:7], v[198:199], v[64:65], v[6:7] op_sel_hi:[0,1,1]
	v_pk_fma_f32 v[10:11], v[198:199], v[66:67], v[10:11] op_sel_hi:[0,1,1]
	v_pk_fma_f32 v[4:5], v[198:199], v[68:69], v[4:5] op_sel_hi:[0,1,1]
	ds_read_b128 v[38:41], v137 offset:896
	ds_read_b128 v[42:45], v137 offset:912
	ds_read_b128 v[46:49], v137 offset:928
	ds_read_b128 v[50:53], v137 offset:944
	ds_read_b128 v[54:57], v137 offset:960
	ds_read_b128 v[58:61], v137 offset:976
	ds_read_b128 v[62:65], v137 offset:992
	ds_read_b128 v[66:69], v137 offset:1008
	s_waitcnt vmcnt(0) lgkmcnt(0)
	v_pk_fma_f32 v[8:9], v[200:201], v[38:39], v[8:9] op_sel_hi:[0,1,1]
	v_pk_fma_f32 v[6:7], v[200:201], v[40:41], v[6:7] op_sel_hi:[0,1,1]
	v_pk_fma_f32 v[10:11], v[200:201], v[42:43], v[10:11] op_sel_hi:[0,1,1]
	v_pk_fma_f32 v[4:5], v[200:201], v[44:45], v[4:5] op_sel_hi:[0,1,1]
	v_pk_fma_f32 v[8:9], v[202:203], v[46:47], v[8:9] op_sel_hi:[0,1,1]
	v_pk_fma_f32 v[6:7], v[202:203], v[48:49], v[6:7] op_sel_hi:[0,1,1]
	v_pk_fma_f32 v[10:11], v[202:203], v[50:51], v[10:11] op_sel_hi:[0,1,1]
	v_pk_fma_f32 v[4:5], v[202:203], v[52:53], v[4:5] op_sel_hi:[0,1,1]
	v_pk_fma_f32 v[8:9], v[204:205], v[54:55], v[8:9] op_sel_hi:[0,1,1]
	v_pk_fma_f32 v[6:7], v[204:205], v[56:57], v[6:7] op_sel_hi:[0,1,1]
	v_pk_fma_f32 v[10:11], v[204:205], v[58:59], v[10:11] op_sel_hi:[0,1,1]
	v_pk_fma_f32 v[4:5], v[204:205], v[60:61], v[4:5] op_sel_hi:[0,1,1]
	v_pk_fma_f32 v[8:9], v[206:207], v[62:63], v[8:9] op_sel_hi:[0,1,1]
	v_pk_fma_f32 v[6:7], v[206:207], v[64:65], v[6:7] op_sel_hi:[0,1,1]
	v_pk_fma_f32 v[10:11], v[206:207], v[66:67], v[10:11] op_sel_hi:[0,1,1]
	v_pk_fma_f32 v[4:5], v[206:207], v[68:69], v[4:5] op_sel_hi:[0,1,1]
	v_add_u32_e32 v137, 0x400, v137
	s_addk_i32 s18, 0x4000
	s_addk_i32 s18, 0x4000
	s_mov_b32 s12, 0x1800000
	s_mov_b32 s13, 0
	v_mov_b32_e32 v14, 40
	s_mul_i32 s12, s0, 0x1800
	v_add_u32_e32 v14, 0, v14
	v_add_u32_e32 v14, 0x20400, v14
	ds_read_b64 v[14:15], v14
	v_add_u32_e32 v38, s12, v12
	v_ashrrev_i32_e32 v39, 31, v38
	s_lshl_b64 s[0:1], s[0:1], 5
	v_lshl_add_u64 v[12:13], v[12:13], 2, s[6:7]
	s_waitcnt lgkmcnt(0)
	v_readfirstlane_b32 s12, v15
	v_readfirstlane_b32 s13, v14
	s_nop 0
	v_mov_b32_e32 v15, s12
	v_mov_b32_e32 v14, s13
	v_lshl_add_u64 v[14:15], v[38:39], 2, v[14:15]
	global_load_dword v50, v[14:15], off
	s_lshl_b32 s12, s15, 3
	s_ashr_i32 s13, s12, 31
	s_add_u32 s0, s0, s12
	s_addc_u32 s12, s1, s13
	v_mad_u64_u32 v[12:13], s[0:1], s0, v227, v[12:13]
	s_mulk_i32 s12, 0x6000
	v_add_co_u32_e32 v14, vcc, s89, v12
	v_add_u32_e32 v13, s12, v13
	s_mov_b64 s[0:1], vcc
	v_add_co_u32_e32 v38, vcc, s80, v12
	v_addc_co_u32_e64 v15, s[0:1], 0, v13, s[0:1]
	s_nop 0
	v_addc_co_u32_e32 v39, vcc, 0, v13, vcc
	v_add_co_u32_e32 v40, vcc, s88, v12
	s_mov_b32 s0, 0x18000
	s_nop 0
	v_addc_co_u32_e32 v41, vcc, 0, v13, vcc
	v_add_co_u32_e32 v42, vcc, s0, v12
	s_waitcnt vmcnt(0) lgkmcnt(0)
	v_add_f32_e32 v8, v8, v50
	v_addc_co_u32_e32 v43, vcc, 0, v13, vcc
	v_add_co_u32_e32 v44, vcc, 0x1e000, v12
	v_add_f32_e32 v9, v9, v50
	s_nop 0
	v_addc_co_u32_e32 v45, vcc, 0, v13, vcc
	v_add_co_u32_e32 v46, vcc, 0x24000, v12
	v_add_f32_e32 v6, v6, v50
	s_nop 0
	v_addc_co_u32_e32 v47, vcc, 0, v13, vcc
	v_add_co_u32_e32 v48, vcc, 0x2a000, v12
	v_add_f32_e32 v7, v7, v50
	s_nop 0
	v_addc_co_u32_e32 v49, vcc, 0, v13, vcc
	v_add_f32_e32 v10, v10, v50
	v_add_f32_e32 v11, v11, v50
	v_add_f32_e32 v4, v4, v50
	v_add_f32_e32 v5, v5, v50
	global_store_dword v[12:13], v8, off
	global_store_dword v[14:15], v9, off
	global_store_dword v[38:39], v6, off
	global_store_dword v[40:41], v7, off
	global_store_dword v[42:43], v10, off
	global_store_dword v[44:45], v11, off
	global_store_dword v[46:47], v4, off
	global_store_dword v[48:49], v5, off
	s_branch .LBB0_572
